# load balance: RoPE-heavy projection tiles moved to the workgroups with one tile fewer; retention and GLA heads interleaved across workgroups in the two linear-attention item loops
# speedup vs baseline: 1.0899x; 1.0108x over previous
.LBB0_75:
	s_add_i32 s5, s17, 0xe40
	s_bitset1_b32 s17, 10
	s_and_b64 s[2:3], s[8:9], exec
	v_and_b32_e32 v42, 7, v66
	v_lshl_add_u32 v40, v42, 5, 0
	s_movk_i32 s3, 0x104
	v_mad_u64_u32 v[52:53], s[8:9], v70, s3, v[40:41]
	ds_read2_b32 v[54:55], v52 offset1:1
	s_waitcnt vmcnt(7)
	v_cvt_f32_f16_sdwa v59, v44 dst_sel:DWORD dst_unused:UNUSED_PAD src0_sel:WORD_1
	v_cvt_f32_f16_e32 v58, v44
	s_cselect_b32 s2, s17, s5
	v_lshlrev_b32_e32 v42, 4, v42
	s_waitcnt lgkmcnt(0)
	v_mul_f32_e32 v43, 0x3fb8aa3b, v54
	v_exp_f32_e32 v56, v43
	v_mul_f32_e32 v43, 0xbfb8aa3b, v54
	v_exp_f32_e32 v54, v43
	v_mul_f32_e32 v43, 0x3fb8aa3b, v55
	v_exp_f32_e32 v57, v43
	v_mul_f32_e32 v43, 0xbfb8aa3b, v55
	v_exp_f32_e32 v55, v43
	s_movk_i32 s5, 0x90
	v_pk_mul_f32 v[56:57], v[56:57], v[58:59]
	v_cvt_f32_f16_sdwa v59, v45 dst_sel:DWORD dst_unused:UNUSED_PAD src0_sel:WORD_1
	v_cvt_pk_f16_f32 v44, v56, v57
	s_waitcnt vmcnt(6)
	v_cvt_f32_f16_sdwa v57, v48 dst_sel:DWORD dst_unused:UNUSED_PAD src0_sel:WORD_1
	v_cvt_f32_f16_e32 v56, v48
	v_cvt_f32_f16_e32 v58, v45
	v_sub_u32_e32 v42, v40, v42
	s_mov_b32 s7, 0x7060302
	v_pk_mul_f32 v[54:55], v[54:55], v[56:57]
	s_lshl_b32 s90, s2, 1
	v_cvt_pk_f16_f32 v48, v54, v55
	ds_read2_b32 v[54:55], v52 offset0:2 offset1:3
	s_waitcnt lgkmcnt(0)
	v_mul_f32_e32 v43, 0x3fb8aa3b, v54
	v_exp_f32_e32 v56, v43
	v_mul_f32_e32 v43, 0xbfb8aa3b, v54
	v_exp_f32_e32 v54, v43
	v_mul_f32_e32 v43, 0x3fb8aa3b, v55
	v_exp_f32_e32 v57, v43
	v_mul_f32_e32 v43, 0xbfb8aa3b, v55
	v_exp_f32_e32 v55, v43
	v_pk_mul_f32 v[56:57], v[56:57], v[58:59]
	s_nop 0
	v_cvt_pk_f16_f32 v45, v56, v57
	v_cvt_f32_f16_sdwa v57, v49 dst_sel:DWORD dst_unused:UNUSED_PAD src0_sel:WORD_1
	v_cvt_f32_f16_e32 v56, v49
	v_cvt_f32_f16_sdwa v59, v46 dst_sel:DWORD dst_unused:UNUSED_PAD src0_sel:WORD_1
	v_cvt_f32_f16_e32 v58, v46
	v_pk_mul_f32 v[54:55], v[54:55], v[56:57]
	s_nop 0
	v_cvt_pk_f16_f32 v49, v54, v55
	ds_read2_b32 v[54:55], v52 offset0:4 offset1:5
	ds_read2_b32 v[52:53], v52 offset0:6 offset1:7
	s_waitcnt lgkmcnt(1)
	v_mul_f32_e32 v43, 0x3fb8aa3b, v54
	v_exp_f32_e32 v56, v43
	v_mul_f32_e32 v43, 0xbfb8aa3b, v54
	v_exp_f32_e32 v54, v43
	v_mul_f32_e32 v43, 0x3fb8aa3b, v55
	v_exp_f32_e32 v57, v43
	v_mul_f32_e32 v43, 0xbfb8aa3b, v55
	v_exp_f32_e32 v55, v43
	s_waitcnt lgkmcnt(0)
	v_mul_f32_e32 v43, 0x3fb8aa3b, v52
	v_pk_mul_f32 v[56:57], v[56:57], v[58:59]
	s_nop 0
	v_cvt_pk_f16_f32 v46, v56, v57
	v_cvt_f32_f16_sdwa v57, v50 dst_sel:DWORD dst_unused:UNUSED_PAD src0_sel:WORD_1
	v_cvt_f32_f16_e32 v56, v50
	v_pk_mul_f32 v[54:55], v[54:55], v[56:57]
	s_nop 0
	v_cvt_pk_f16_f32 v50, v54, v55
	v_exp_f32_e32 v54, v43
	v_mul_f32_e32 v43, 0xbfb8aa3b, v52
	v_exp_f32_e32 v52, v43
	v_mul_f32_e32 v43, 0x3fb8aa3b, v53
	v_exp_f32_e32 v55, v43
	v_cvt_f32_f16_sdwa v57, v47 dst_sel:DWORD dst_unused:UNUSED_PAD src0_sel:WORD_1
	v_cvt_f32_f16_e32 v56, v47
	v_mul_f32_e32 v43, 0xbfb8aa3b, v53
	v_exp_f32_e32 v53, v43
	v_mul_lo_u32 v43, v70, s5
	v_pk_mul_f32 v[54:55], v[54:55], v[56:57]
	s_nop 0
	v_cvt_pk_f16_f32 v47, v54, v55
	v_cvt_f32_f16_sdwa v55, v51 dst_sel:DWORD dst_unused:UNUSED_PAD src0_sel:WORD_1
	v_cvt_f32_f16_e32 v54, v51
	v_pk_mul_f32 v[52:53], v[52:53], v[54:55]
	s_nop 0
	v_cvt_pk_f16_f32 v51, v52, v53
	v_add_u32_e32 v52, v42, v43
	ds_write_b128 v52, v[44:47] offset:24832
	ds_write_b128 v52, v[48:51] offset:34048
	v_mad_u64_u32 v[44:45], s[8:9], v69, s3, v[40:41]
	ds_read2_b32 v[46:47], v44 offset1:1
	s_waitcnt vmcnt(5)
	v_cvt_f32_f16_sdwa v51, v36 dst_sel:DWORD dst_unused:UNUSED_PAD src0_sel:WORD_1
	v_cvt_f32_f16_e32 v50, v36
	s_mov_b32 s3, 0x1fffffe
	s_waitcnt lgkmcnt(0)
	v_mul_f32_e32 v40, 0x3fb8aa3b, v46
	v_exp_f32_e32 v48, v40
	v_mul_f32_e32 v40, 0xbfb8aa3b, v46
	v_exp_f32_e32 v46, v40
	v_mul_f32_e32 v40, 0x3fb8aa3b, v47
	v_exp_f32_e32 v49, v40
	v_mul_f32_e32 v40, 0xbfb8aa3b, v47
	v_exp_f32_e32 v47, v40
	v_pk_mul_f32 v[48:49], v[48:49], v[50:51]
	s_nop 0
	v_cvt_pk_f16_f32 v36, v48, v49
	s_waitcnt vmcnt(4)
	v_cvt_f32_f16_sdwa v49, v32 dst_sel:DWORD dst_unused:UNUSED_PAD src0_sel:WORD_1
	v_cvt_f32_f16_e32 v48, v32
	v_cvt_f32_f16_sdwa v51, v37 dst_sel:DWORD dst_unused:UNUSED_PAD src0_sel:WORD_1
	v_cvt_f32_f16_e32 v50, v37
	v_pk_mul_f32 v[46:47], v[46:47], v[48:49]
	s_nop 0
	v_cvt_pk_f16_f32 v32, v46, v47
	ds_read2_b32 v[46:47], v44 offset0:2 offset1:3
	s_waitcnt lgkmcnt(0)
	v_mul_f32_e32 v40, 0x3fb8aa3b, v46
	v_exp_f32_e32 v48, v40
	v_mul_f32_e32 v40, 0xbfb8aa3b, v46
	v_exp_f32_e32 v46, v40
	v_mul_f32_e32 v40, 0x3fb8aa3b, v47
	v_exp_f32_e32 v49, v40
	v_mul_f32_e32 v40, 0xbfb8aa3b, v47
	v_exp_f32_e32 v47, v40
	v_pk_mul_f32 v[48:49], v[48:49], v[50:51]
	s_nop 0
	v_cvt_pk_f16_f32 v37, v48, v49
	v_cvt_f32_f16_sdwa v49, v33 dst_sel:DWORD dst_unused:UNUSED_PAD src0_sel:WORD_1
	v_cvt_f32_f16_e32 v48, v33
	v_cvt_f32_f16_sdwa v51, v38 dst_sel:DWORD dst_unused:UNUSED_PAD src0_sel:WORD_1
	v_cvt_f32_f16_e32 v50, v38
	v_pk_mul_f32 v[46:47], v[46:47], v[48:49]
	s_nop 0
	v_cvt_pk_f16_f32 v33, v46, v47
	ds_read2_b32 v[46:47], v44 offset0:4 offset1:5
	ds_read2_b32 v[44:45], v44 offset0:6 offset1:7
	s_waitcnt lgkmcnt(1)
	v_mul_f32_e32 v40, 0x3fb8aa3b, v46
	v_exp_f32_e32 v48, v40
	v_mul_f32_e32 v40, 0xbfb8aa3b, v46
	v_exp_f32_e32 v46, v40
	v_mul_f32_e32 v40, 0x3fb8aa3b, v47
	v_exp_f32_e32 v49, v40
	v_mul_f32_e32 v40, 0xbfb8aa3b, v47
	v_exp_f32_e32 v47, v40
	s_waitcnt lgkmcnt(0)
	v_mul_f32_e32 v40, 0x3fb8aa3b, v44
	v_pk_mul_f32 v[48:49], v[48:49], v[50:51]
	v_mov_b32_e32 v50, v41
	v_cvt_pk_f16_f32 v38, v48, v49
	v_cvt_f32_f16_sdwa v49, v34 dst_sel:DWORD dst_unused:UNUSED_PAD src0_sel:WORD_1
	v_cvt_f32_f16_e32 v48, v34
	v_mov_b32_e32 v51, v41
	v_pk_mul_f32 v[46:47], v[46:47], v[48:49]
	s_nop 0
	v_cvt_pk_f16_f32 v34, v46, v47
	v_exp_f32_e32 v46, v40
	v_mul_f32_e32 v40, 0xbfb8aa3b, v44
	v_exp_f32_e32 v44, v40
	v_mul_f32_e32 v40, 0x3fb8aa3b, v45
	v_exp_f32_e32 v47, v40
	v_cvt_f32_f16_sdwa v49, v39 dst_sel:DWORD dst_unused:UNUSED_PAD src0_sel:WORD_1
	v_cvt_f32_f16_e32 v48, v39
	v_mul_f32_e32 v40, 0xbfb8aa3b, v45
	v_exp_f32_e32 v45, v40
	v_mul_lo_u32 v40, v69, s5
	v_pk_mul_f32 v[46:47], v[46:47], v[48:49]
	v_add_u32_e32 v42, v42, v40
	v_cvt_pk_f16_f32 v39, v46, v47
	v_cvt_f32_f16_sdwa v47, v35 dst_sel:DWORD dst_unused:UNUSED_PAD src0_sel:WORD_1
	v_cvt_f32_f16_e32 v46, v35
	v_mov_b32_e32 v48, v41
	v_mov_b32_e32 v49, v41
	v_pk_mul_f32 v[44:45], v[44:45], v[46:47]
	s_nop 0
	v_cvt_pk_f16_f32 v35, v44, v45
	ds_write_b128 v42, v[36:39] offset:24832
	ds_write_b128 v42, v[32:35] offset:34048
	v_mbcnt_lo_u32_b32 v32, -1, 0
	v_mbcnt_hi_u32_b32 v32, -1, v32
	v_mov_b32_e32 v44, v41
	v_or_b32_e32 v33, s55, v32
	v_bfe_u32 v34, v32, 5, 1
	v_lshrrev_b32_e32 v33, 5, v33
	v_and_or_b32 v33, v33, s3, v34
	v_lshlrev_b32_e32 v32, 2, v32
	v_and_b32_e32 v32, 0x7c, v32
	v_mul_lo_u32 v33, v33, s67
	s_mov_b32 s3, 0x5040100
	v_add3_u32 v32, 0, v32, v33
	v_perm_b32 v34, v12, v8, s3
	v_perm_b32 v8, v12, v8, s7
	v_add_u32_e32 v12, 0xcc00, v32
	ds_write2_b32 v12, v34, v8 offset0:64 offset1:100
	v_perm_b32 v8, v13, v9, s3
	v_perm_b32 v9, v13, v9, s7
	ds_write2_b32 v12, v8, v9 offset0:136 offset1:172
	v_perm_b32 v8, v14, v10, s3
	v_perm_b32 v9, v14, v10, s7
	ds_write2_b32 v12, v8, v9 offset0:208 offset1:244
	v_perm_b32 v8, v15, v11, s3
	v_perm_b32 v9, v15, v11, s7
	v_add_u32_e32 v10, 0xd000, v32
	ds_write2_b32 v10, v8, v9 offset0:24 offset1:60
	v_perm_b32 v8, v4, v0, s3
	v_perm_b32 v0, v4, v0, s7
	v_add_u32_e32 v4, 0xf000, v32
	ds_write2_b32 v4, v8, v0 offset0:64 offset1:100
	v_perm_b32 v0, v5, v1, s3
	v_perm_b32 v1, v5, v1, s7
	ds_write2_b32 v4, v0, v1 offset0:136 offset1:172
	v_perm_b32 v0, v6, v2, s3
	v_perm_b32 v1, v6, v2, s7
	ds_write2_b32 v4, v0, v1 offset0:208 offset1:244
	v_perm_b32 v0, v7, v3, s3
	v_perm_b32 v1, v7, v3, s7
	v_add_u32_e32 v2, 0xf400, v32
	v_readlane_b32 s7, v255, 29
	ds_write2_b32 v2, v0, v1 offset0:24 offset1:60
	v_ashrrev_i32_e32 v32, 2, v67
	v_lshl_add_u32 v0, v68, 1, s7
	v_add_u32_e32 v1, v0, v43
	s_waitcnt vmcnt(3)
	ds_write_b128 v1, v[20:23]
	v_add_u32_e32 v1, v0, v40
	s_waitcnt vmcnt(2)
	ds_write_b128 v1, v[16:19]
	v_add_u32_e32 v1, 0x200, v67
	v_lshrrev_b32_e32 v1, 3, v1
	v_mad_u64_u32 v[2:3], s[8:9], v1, s5, v[0:1]
	v_add_u32_e32 v1, 0x300, v67
	v_lshrrev_b32_e32 v1, 3, v1
	s_movk_i32 s3, 0xffe0
	s_waitcnt vmcnt(1)
	ds_write_b128 v2, v[28:31]
	v_mad_u64_u32 v[0:1], s[8:9], v1, s5, v[0:1]
	v_bfi_b32 v2, s3, v32, v66
	s_waitcnt vmcnt(0)
	ds_write_b128 v0, v[24:27]
	v_bfe_u32 v0, v67, 6, 1
	v_and_b32_e32 v1, 31, v66
	v_mul_lo_u32 v36, v2, s5
	v_lshrrev_b32_e32 v2, 1, v66
	v_and_b32_e32 v37, 16, v2
	v_lshl_or_b32 v39, v0, 5, v1
	v_mov_b32_e32 v18, v41
	v_mov_b32_e32 v19, v41
	v_mov_b32_e32 v20, v41
	v_mov_b32_e32 v21, v41
	v_mov_b32_e32 v22, v41
	v_mov_b32_e32 v23, v41
	v_mov_b32_e32 v24, v41
	v_mov_b32_e32 v25, v41
	v_mov_b32_e32 v26, v41
	v_mov_b32_e32 v27, v41
	v_mov_b32_e32 v28, v41
	v_mov_b32_e32 v29, v41
	v_mov_b32_e32 v30, v41
	v_mov_b32_e32 v31, v41
	v_mov_b32_e32 v33, v41
	v_mov_b32_e32 v34, v41
	v_add3_u32 v38, 0, v36, v37
	v_mad_u32_u24 v40, v39, s5, 0
	s_waitcnt lgkmcnt(0)
	s_barrier
	v_add_u32_e32 v42, v40, v37
	ds_read_b128 v[2:5], v38 offset:24832
	ds_read_b128 v[6:9], v38 offset:24864
	ds_read_b128 v[10:13], v42 offset:34048
	ds_read_b128 v[14:17], v42 offset:34080
	v_accvgpr_write_b32 a0, v18
	v_accvgpr_write_b32 a1, v19
	v_accvgpr_write_b32 a2, v20
	v_accvgpr_write_b32 a3, v21
	v_accvgpr_write_b32 a4, v22
	v_accvgpr_write_b32 a5, v23
	v_accvgpr_write_b32 a6, v24
	v_accvgpr_write_b32 a7, v25
	v_accvgpr_write_b32 a8, v26
	v_accvgpr_write_b32 a9, v27
	v_accvgpr_write_b32 a10, v28
	v_accvgpr_write_b32 a11, v29
	v_accvgpr_write_b32 a12, v30
	v_accvgpr_write_b32 a13, v31
	v_accvgpr_write_b32 a14, v33
	v_accvgpr_write_b32 a15, v34
	v_and_b32_e32 v35, 0xffffffe0, v32
	v_mov_b32_e32 v18, v41
	s_waitcnt lgkmcnt(1)
	v_mfma_f32_32x32x16_f16 a[0:15], v[2:5], v[10:13], a[0:15]
	v_mov_b32_e32 v19, v41
	v_mov_b32_e32 v20, v41
	v_mov_b32_e32 v21, v41
	v_mov_b32_e32 v22, v41
	v_mov_b32_e32 v23, v41
	v_mov_b32_e32 v24, v41
	v_mov_b32_e32 v25, v41
	s_waitcnt lgkmcnt(0)
	v_mfma_f32_32x32x16_f16 a[0:15], v[6:9], v[14:17], a[0:15]
	ds_read_b128 v[2:5], v38 offset:24896
	ds_read_b128 v[6:9], v42 offset:34112
	v_mov_b32_e32 v16, v41
	v_mov_b32_e32 v17, v41
	v_mov_b32_e32 v26, v41
	v_mov_b32_e32 v27, v41
	v_mov_b32_e32 v28, v41
	v_mov_b32_e32 v29, v41
	s_waitcnt lgkmcnt(0)
	v_mfma_f32_32x32x16_f16 a[0:15], v[2:5], v[6:9], a[0:15]
	ds_read_b128 v[2:5], v38 offset:24928
	ds_read_b128 v[6:9], v42 offset:34144
	v_mov_b32_e32 v30, v41
	v_mov_b32_e32 v33, v41
	v_mov_b32_e32 v34, v41
	v_mov_b32_e32 v38, v41
	v_mov_b32_e32 v42, v41
	v_mov_b32_e32 v43, v41
	s_waitcnt lgkmcnt(0)
	v_mfma_f32_32x32x16_f16 a[0:15], v[2:5], v[6:9], a[0:15]
	v_lshrrev_b32_e32 v2, 3, v66
	v_and_or_b32 v2, v2, 4, v35
	v_mul_i32_i24_e32 v3, 0xffffff72, v39
	v_mul_lo_u32 v5, v2, s5
	v_add3_u32 v3, v40, v3, v5
	v_cmp_le_i32_e32 vcc, v39, v2
	v_add_u32_e32 v8, 0, v37
	v_mov_b32_e32 v35, v41
	v_mov_b32_e32 v40, v41
	v_mov_b32_e32 v45, v41
	v_mov_b32_e32 v46, v41
	v_mov_b32_e32 v47, v41
	v_accvgpr_read_b32 v4, a0
	v_cvt_f16_f32_e32 v4, v4
	v_accvgpr_read_b32 v5, a1
	v_cvt_f16_f32_e32 v5, v5
	v_add_u32_e32 v36, v8, v36
	v_cndmask_b32_e32 v4, 0, v4, vcc
	ds_write_b16 v3, v4 offset:43264
	v_or_b32_e32 v4, 1, v2
	v_cmp_le_i32_e32 vcc, v39, v4
	v_readlane_b32 s3, v255, 30
	s_movk_i32 s5, 0x210
	v_cndmask_b32_e32 v4, 0, v5, vcc
	v_accvgpr_read_b32 v5, a2
	v_cvt_f16_f32_e32 v5, v5
	ds_write_b16 v3, v4 offset:43408
	v_or_b32_e32 v4, 2, v2
	v_cmp_le_i32_e32 vcc, v39, v4
	s_nop 1
	v_cndmask_b32_e32 v4, 0, v5, vcc
	v_accvgpr_read_b32 v5, a3
	v_cvt_f16_f32_e32 v5, v5
	ds_write_b16 v3, v4 offset:43552
	v_or_b32_e32 v4, 3, v2
	v_cmp_le_i32_e32 vcc, v39, v4
	s_nop 1
	v_cndmask_b32_e32 v4, 0, v5, vcc
	v_accvgpr_read_b32 v5, a4
	v_cvt_f16_f32_e32 v5, v5
	ds_write_b16 v3, v4 offset:43696
	v_or_b32_e32 v4, 8, v2
	v_cmp_le_i32_e32 vcc, v39, v4
	s_nop 1
	v_cndmask_b32_e32 v4, 0, v5, vcc
	v_accvgpr_read_b32 v5, a5
	v_cvt_f16_f32_e32 v5, v5
	ds_write_b16 v3, v4 offset:44416
	v_or_b32_e32 v4, 9, v2
	v_cmp_le_i32_e32 vcc, v39, v4
	s_nop 1
	v_cndmask_b32_e32 v4, 0, v5, vcc
	v_accvgpr_read_b32 v5, a6
	v_cvt_f16_f32_e32 v5, v5
	ds_write_b16 v3, v4 offset:44560
	v_or_b32_e32 v4, 10, v2
	v_cmp_le_i32_e32 vcc, v39, v4
	s_nop 1
	v_cndmask_b32_e32 v4, 0, v5, vcc
	v_accvgpr_read_b32 v5, a7
	v_cvt_f16_f32_e32 v5, v5
	ds_write_b16 v3, v4 offset:44704
	v_or_b32_e32 v4, 11, v2
	v_cmp_le_i32_e32 vcc, v39, v4
	s_nop 1
	v_cndmask_b32_e32 v4, 0, v5, vcc
	v_accvgpr_read_b32 v5, a8
	v_cvt_f16_f32_e32 v5, v5
	ds_write_b16 v3, v4 offset:44848
	v_or_b32_e32 v4, 16, v2
	v_cmp_le_i32_e32 vcc, v39, v4
	s_nop 1
	v_cndmask_b32_e32 v4, 0, v5, vcc
	v_accvgpr_read_b32 v5, a9
	v_cvt_f16_f32_e32 v5, v5
	ds_write_b16 v3, v4 offset:45568
	v_or_b32_e32 v4, 17, v2
	v_cmp_le_i32_e32 vcc, v39, v4
	s_nop 1
	v_cndmask_b32_e32 v4, 0, v5, vcc
	v_accvgpr_read_b32 v5, a10
	v_cvt_f16_f32_e32 v5, v5
	ds_write_b16 v3, v4 offset:45712
	v_or_b32_e32 v4, 18, v2
	v_cmp_le_i32_e32 vcc, v39, v4
	s_nop 1
	v_cndmask_b32_e32 v4, 0, v5, vcc
	v_accvgpr_read_b32 v5, a11
	v_cvt_f16_f32_e32 v5, v5
	ds_write_b16 v3, v4 offset:45856
	v_or_b32_e32 v4, 19, v2
	v_cmp_le_i32_e32 vcc, v39, v4
	s_nop 1
	v_cndmask_b32_e32 v4, 0, v5, vcc
	v_accvgpr_read_b32 v5, a12
	v_cvt_f16_f32_e32 v5, v5
	ds_write_b16 v3, v4 offset:46000
	v_or_b32_e32 v4, 24, v2
	v_cmp_le_i32_e32 vcc, v39, v4
	s_nop 1
	v_cndmask_b32_e32 v4, 0, v5, vcc
	v_accvgpr_read_b32 v5, a13
	v_cvt_f16_f32_e32 v5, v5
	ds_write_b16 v3, v4 offset:46720
	v_or_b32_e32 v4, 25, v2
	v_cmp_le_i32_e32 vcc, v39, v4
	s_nop 1
	v_cndmask_b32_e32 v4, 0, v5, vcc
	v_accvgpr_read_b32 v5, a14
	v_cvt_f16_f32_e32 v5, v5
	ds_write_b16 v3, v4 offset:46864
	v_or_b32_e32 v4, 26, v2
	v_cmp_le_i32_e32 vcc, v39, v4
	s_nop 1
	v_cndmask_b32_e32 v4, 0, v5, vcc
	v_accvgpr_read_b32 v5, a15
	v_cvt_f16_f32_e32 v5, v5
	ds_write_b16 v3, v4 offset:47008
	v_or_b32_e32 v4, 27, v2
	v_cmp_le_i32_e32 vcc, v39, v4
	v_mov_b32_e32 v39, v41
	v_mul_lo_u32 v2, v2, s5
	v_cndmask_b32_e32 v4, 0, v5, vcc
	ds_write_b16 v3, v4 offset:47152
	v_mov_b32_e32 v3, v41
	v_lshl_or_b32 v4, v0, 6, v1
	s_waitcnt lgkmcnt(0)
	s_barrier
	v_mul_u32_u24_e32 v9, 0x48, v4
	ds_read_b128 v[4:7], v36 offset:43264
	v_lshlrev_b32_e32 v9, 1, v9
	v_add_u32_e32 v52, v8, v9
	v_add3_u32 v37, s7, v37, v9
	ds_read_b128 v[8:11], v52 offset:52480
	ds_read_b128 v[12:15], v52 offset:52512
	v_accvgpr_write_b32 a0, v3
	v_accvgpr_write_b32 a1, v16
	v_accvgpr_write_b32 a2, v17
	v_accvgpr_write_b32 a3, v18
	v_accvgpr_write_b32 a4, v19
	v_accvgpr_write_b32 a5, v20
	v_accvgpr_write_b32 a6, v21
	v_accvgpr_write_b32 a7, v22
	v_accvgpr_write_b32 a8, v23
	v_accvgpr_write_b32 a9, v24
	v_accvgpr_write_b32 a10, v25
	v_accvgpr_write_b32 a11, v26
	v_accvgpr_write_b32 a12, v27
	v_accvgpr_write_b32 a13, v28
	v_accvgpr_write_b32 a14, v29
	v_accvgpr_write_b32 a15, v30
	v_accvgpr_write_b32 a16, v33
	v_accvgpr_write_b32 a17, v34
	s_waitcnt lgkmcnt(1)
	v_mfma_f32_32x32x16_f16 a[0:15], v[4:7], v[8:11], a[0:15]
	ds_read_b128 v[8:11], v36 offset:24832
	ds_read_b128 v[16:19], v36 offset:24864
	ds_read_b128 v[20:23], v37
	ds_read_b128 v[24:27], v37 offset:32
	v_accvgpr_write_b32 a18, v35
	v_accvgpr_write_b32 a19, v38
	v_accvgpr_write_b32 a20, v39
	v_accvgpr_write_b32 a21, v40
	v_accvgpr_write_b32 a22, v42
	v_accvgpr_write_b32 a23, v43
	s_waitcnt lgkmcnt(1)
	v_mfma_f32_32x32x16_f16 a[0:15], v[8:11], v[20:23], a[0:15]
	ds_read_b128 v[20:23], v52 offset:57088
	ds_read_b128 v[28:31], v37 offset:4608
	v_accvgpr_write_b32 a24, v44
	v_accvgpr_write_b32 a25, v45
	v_accvgpr_write_b32 a26, v46
	v_accvgpr_write_b32 a27, v47
	v_accvgpr_write_b32 a28, v48
	v_accvgpr_write_b32 a29, v49
	v_accvgpr_write_b32 a30, v50
	v_accvgpr_write_b32 a31, v51
	v_lshl_add_u32 v0, v0, 8, s3
	v_lshlrev_b32_e32 v1, 2, v1
	s_waitcnt lgkmcnt(1)
	v_mfma_f32_32x32x16_f16 a[16:31], v[4:7], v[20:23], a[16:31]
	ds_read_b128 v[4:7], v36 offset:43296
	v_add3_u32 v0, v0, v1, v2
	v_and_b32_e32 v40, 3, v66
	v_lshlrev_b32_e32 v1, 7, v40
	v_lshlrev_b32_e32 v40, 6, v40
	s_mov_b32 s7, s91
	s_waitcnt lgkmcnt(1)
	v_mfma_f32_32x32x16_f16 a[16:31], v[8:11], v[28:31], a[16:31]
	s_waitcnt lgkmcnt(0)
	v_mfma_f32_32x32x16_f16 a[0:15], v[4:7], v[12:15], a[0:15]
	ds_read_b128 v[8:11], v52 offset:57120
	ds_read_b128 v[12:15], v37 offset:4640
	s_waitcnt lgkmcnt(1)
	v_mfma_f32_32x32x16_f16 a[16:31], v[4:7], v[8:11], a[16:31]
	v_mfma_f32_32x32x16_f16 a[0:15], v[16:19], v[24:27], a[0:15]
	s_waitcnt lgkmcnt(0)
	v_mfma_f32_32x32x16_f16 a[16:31], v[16:19], v[12:15], a[16:31]
	ds_read_b128 v[4:7], v36 offset:43328
	ds_read_b128 v[8:11], v36 offset:24896
	ds_read_b128 v[12:15], v52 offset:52544
	ds_read_b128 v[16:19], v37 offset:64
	s_waitcnt lgkmcnt(1)
	v_mfma_f32_32x32x16_f16 a[0:15], v[4:7], v[12:15], a[0:15]
	s_waitcnt lgkmcnt(0)
	v_mfma_f32_32x32x16_f16 a[0:15], v[8:11], v[16:19], a[0:15]
	ds_read_b128 v[12:15], v52 offset:57152
	ds_read_b128 v[16:19], v37 offset:4672
	s_waitcnt lgkmcnt(1)
	v_mfma_f32_32x32x16_f16 a[16:31], v[4:7], v[12:15], a[16:31]
	s_waitcnt lgkmcnt(0)
	v_mfma_f32_32x32x16_f16 a[16:31], v[8:11], v[16:19], a[16:31]
	ds_read_b128 v[4:7], v36 offset:43360
	ds_read_b128 v[8:11], v36 offset:24928
	ds_read_b128 v[12:15], v52 offset:52576
	ds_read_b128 v[16:19], v37 offset:96
	s_waitcnt lgkmcnt(1)
	v_mfma_f32_32x32x16_f16 a[0:15], v[4:7], v[12:15], a[0:15]
	s_waitcnt lgkmcnt(0)
	v_mfma_f32_32x32x16_f16 a[0:15], v[8:11], v[16:19], a[0:15]
	ds_read_b128 v[12:15], v52 offset:57184
	ds_read_b128 v[16:19], v37 offset:4704
	s_waitcnt lgkmcnt(1)
	v_mfma_f32_32x32x16_f16 a[16:31], v[4:7], v[12:15], a[16:31]
	s_waitcnt lgkmcnt(0)
	v_mfma_f32_32x32x16_f16 a[16:31], v[8:11], v[16:19], a[16:31]
	s_nop 5
	ds_write_b32 v0, a0
	ds_write_b32 v0, a1 offset:528
	ds_write_b32 v0, a2 offset:1056
	ds_write_b32 v0, a3 offset:1584
	ds_write_b32 v0, a4 offset:4224
	ds_write_b32 v0, a5 offset:4752
	ds_write_b32 v0, a6 offset:5280
	ds_write_b32 v0, a7 offset:5808
	ds_write_b32 v0, a8 offset:8448
	ds_write_b32 v0, a9 offset:8976
	ds_write_b32 v0, a10 offset:9504
	ds_write_b32 v0, a11 offset:10032
	ds_write_b32 v0, a12 offset:12672
	ds_write_b32 v0, a13 offset:13200
	ds_write_b32 v0, a14 offset:13728
	ds_write_b32 v0, a15 offset:14256
	ds_write_b32 v0, a16 offset:128
	ds_write_b32 v0, a17 offset:656
	ds_write_b32 v0, a18 offset:1184
	ds_write_b32 v0, a19 offset:1712
	ds_write_b32 v0, a20 offset:4352
	ds_write_b32 v0, a21 offset:4880
	ds_write_b32 v0, a22 offset:5408
	ds_write_b32 v0, a23 offset:5936
	ds_write_b32 v0, a24 offset:8576
	ds_write_b32 v0, a25 offset:9104
	ds_write_b32 v0, a26 offset:9632
	ds_write_b32 v0, a27 offset:10160
	ds_write_b32 v0, a28 offset:12800
	ds_write_b32 v0, a29 offset:13328
	ds_write_b32 v0, a30 offset:13856
	ds_write_b32 v0, a31 offset:14384
	v_mul_lo_u32 v0, v32, s5
	v_add3_u32 v33, s3, v0, v1
	s_waitcnt lgkmcnt(0)
	s_barrier
	ds_read_b128 v[28:31], v33
	ds_read_b128 v[24:27], v33 offset:16
	ds_read_b128 v[20:23], v33 offset:32
	ds_read_b128 v[16:19], v33 offset:48
	ds_read_b128 v[12:15], v33 offset:64
	ds_read_b128 v[8:11], v33 offset:80
	s_waitcnt lgkmcnt(5)
	v_mov_b32_e32 v2, v29
	s_waitcnt lgkmcnt(4)
	v_mov_b32_e32 v3, v25
	v_mov_b32_e32 v0, v28
	v_mov_b32_e32 v1, v24
	v_pk_mul_f32 v[2:3], v[2:3], v[2:3]
	s_nop 0
	v_pk_fma_f32 v[0:1], v[0:1], v[0:1], v[2:3]
	v_mov_b32_e32 v2, v30
	v_mov_b32_e32 v3, v26
	v_pk_fma_f32 v[0:1], v[2:3], v[2:3], v[0:1]
	v_mov_b32_e32 v2, v31
	v_mov_b32_e32 v3, v27
	v_pk_fma_f32 v[34:35], v[2:3], v[2:3], v[0:1]
	s_waitcnt lgkmcnt(3)
	v_mov_b32_e32 v2, v21
	s_waitcnt lgkmcnt(2)
	v_mov_b32_e32 v3, v17
	v_mov_b32_e32 v0, v20
	v_mov_b32_e32 v1, v16
	v_pk_mul_f32 v[2:3], v[2:3], v[2:3]
	s_nop 0
	v_pk_fma_f32 v[0:1], v[0:1], v[0:1], v[2:3]
	v_mov_b32_e32 v2, v22
	v_mov_b32_e32 v3, v18
	v_pk_fma_f32 v[0:1], v[2:3], v[2:3], v[0:1]
	v_mov_b32_e32 v2, v23
	v_mov_b32_e32 v3, v19
	v_pk_fma_f32 v[36:37], v[2:3], v[2:3], v[0:1]
	s_waitcnt lgkmcnt(1)
	v_mov_b32_e32 v2, v13
	s_waitcnt lgkmcnt(0)
	v_mov_b32_e32 v3, v9
	v_mov_b32_e32 v0, v12
	v_mov_b32_e32 v1, v8
	v_pk_mul_f32 v[2:3], v[2:3], v[2:3]
	s_nop 0
	v_pk_fma_f32 v[0:1], v[0:1], v[0:1], v[2:3]
	v_mov_b32_e32 v2, v14
	v_mov_b32_e32 v3, v10
	v_pk_fma_f32 v[0:1], v[2:3], v[2:3], v[0:1]
	v_mov_b32_e32 v2, v15
	v_mov_b32_e32 v3, v11
	v_pk_fma_f32 v[38:39], v[2:3], v[2:3], v[0:1]
	ds_read_b128 v[4:7], v33 offset:96
	ds_read_b128 v[0:3], v33 offset:112
	v_add_f32_e32 v33, v34, v35
	v_add_f32_e32 v33, v33, v36
	v_add_f32_e32 v33, v33, v37
	s_waitcnt lgkmcnt(1)
	v_mov_b32_e32 v44, v5
	s_waitcnt lgkmcnt(0)
	v_mov_b32_e32 v45, v1
	v_mov_b32_e32 v42, v4
	v_mov_b32_e32 v43, v0
	v_pk_mul_f32 v[44:45], v[44:45], v[44:45]
	v_add_f32_e32 v33, v33, v38
	v_pk_fma_f32 v[42:43], v[42:43], v[42:43], v[44:45]
	v_mov_b32_e32 v44, v6
	v_mov_b32_e32 v45, v2
	v_pk_fma_f32 v[42:43], v[44:45], v[44:45], v[42:43]
	v_mov_b32_e32 v44, v7
	v_mov_b32_e32 v45, v3
	v_pk_fma_f32 v[42:43], v[44:45], v[44:45], v[42:43]
	v_add_f32_e32 v33, v33, v39
	v_add_f32_e32 v33, v33, v42
	v_add_f32_e32 v33, v33, v43
	v_mov_b32_e32 v34, 0x358637bd
	s_nop 0
	v_add_f32_dpp v33, v33, v33 quad_perm:[1,0,3,2] row_mask:0xf bank_mask:0xf bound_ctrl:1
	s_nop 1
	v_add_f32_dpp v33, v33, v33 quad_perm:[2,3,0,1] row_mask:0xf bank_mask:0xf bound_ctrl:1
	v_fmamk_f32 v33, v33, 0x3c000000, v34
	v_cmp_gt_f32_e32 vcc, s70, v33
	v_mul_f32_e32 v34, 0x4b800000, v33
	s_nop 0
	v_cndmask_b32_e32 v33, v33, v34, vcc
	v_rsq_f32_e32 v33, v33
	s_nop 0
	v_mul_f32_e32 v34, 0x45800000, v33
	v_cndmask_b32_e32 v36, v33, v34, vcc
	v_add_u32_e32 v34, s16, v32
	v_mov_b64_e32 v[32:33], s[56:57]
	v_mad_i64_i32 v[32:33], s[8:9], v34, s68, v[32:33]
	v_lshl_add_u64 v[32:33], v[32:33], 0, s[90:91]
	v_lshl_add_u64 v[42:43], v[32:33], 0, v[40:41]
	v_mov_b64_e32 v[32:33], s[96:97]
	v_mad_i64_i32 v[32:33], s[2:3], v34, s64, v[32:33]
	v_lshl_add_u64 v[32:33], s[6:7], 1, v[32:33]
	v_lshl_add_u64 v[38:39], v[32:33], 0, v[40:41]
	global_load_dwordx4 v[32:35], v[42:43], off
	v_pk_mul_f32 v[28:29], v[28:29], v[36:37] op_sel_hi:[1,0]
	v_pk_mul_f32 v[30:31], v[30:31], v[36:37] op_sel_hi:[1,0]
	v_pk_mul_f32 v[24:25], v[24:25], v[36:37] op_sel_hi:[1,0]
	v_pk_mul_f32 v[20:21], v[20:21], v[36:37] op_sel_hi:[1,0]
	v_pk_mul_f32 v[22:23], v[22:23], v[36:37] op_sel_hi:[1,0]
	v_pk_mul_f32 v[16:17], v[16:17], v[36:37] op_sel_hi:[1,0]
	v_pk_mul_f32 v[12:13], v[12:13], v[36:37] op_sel_hi:[1,0]
	v_pk_mul_f32 v[14:15], v[14:15], v[36:37] op_sel_hi:[1,0]
	v_pk_mul_f32 v[8:9], v[8:9], v[36:37] op_sel_hi:[1,0]
	v_pk_mul_f32 v[4:5], v[4:5], v[36:37] op_sel_hi:[1,0]
	v_pk_mul_f32 v[6:7], v[6:7], v[36:37] op_sel_hi:[1,0]
	v_pk_mul_f32 v[0:1], v[0:1], v[36:37] op_sel_hi:[1,0]
	v_readlane_b32 s8, v253, 2
	v_readlane_b32 s10, v253, 4
	s_bfe_u32 s9, s4, 0x10008
	s_lshl_b32 s9, s9, 2
	s_xor_b32 s4, s4, s9
	s_add_i32 s4, s4, s10
	s_cmpk_gt_i32 s4, 0x7ff
	v_readlane_b32 s9, v253, 3
	v_readlane_b32 s11, v253, 5
	s_waitcnt vmcnt(0)
	v_cvt_f32_f16_e32 v44, v32
	v_cvt_f32_f16_sdwa v45, v32 dst_sel:DWORD dst_unused:UNUSED_PAD src0_sel:WORD_1
	v_cvt_f32_f16_e32 v32, v33
	v_cvt_f32_f16_sdwa v33, v33 dst_sel:DWORD dst_unused:UNUSED_PAD src0_sel:WORD_1
	v_pk_mul_f32 v[28:29], v[28:29], v[44:45]
	s_nop 0
	v_cvt_pk_f16_f32 v28, v28, v29
	v_pk_mul_f32 v[30:31], v[30:31], v[32:33]
	s_nop 0
	v_cvt_pk_f16_f32 v29, v30, v31
	v_cvt_f32_f16_e32 v30, v34
	v_cvt_f32_f16_sdwa v31, v34 dst_sel:DWORD dst_unused:UNUSED_PAD src0_sel:WORD_1
	v_pk_mul_f32 v[24:25], v[24:25], v[30:31]
	s_nop 0
	v_cvt_pk_f16_f32 v30, v24, v25
	v_pk_mul_f32 v[24:25], v[26:27], v[36:37] op_sel_hi:[1,0]
	v_cvt_f32_f16_e32 v26, v35
	v_cvt_f32_f16_sdwa v27, v35 dst_sel:DWORD dst_unused:UNUSED_PAD src0_sel:WORD_1
	v_pk_mul_f32 v[24:25], v[24:25], v[26:27]
	s_nop 0
	v_cvt_pk_f16_f32 v31, v24, v25
	global_store_dwordx4 v[38:39], v[28:31], off
	global_load_dwordx4 v[24:27], v[42:43], off offset:16
	s_waitcnt vmcnt(0)
	v_cvt_f32_f16_e32 v28, v24
	v_cvt_f32_f16_sdwa v29, v24 dst_sel:DWORD dst_unused:UNUSED_PAD src0_sel:WORD_1
	v_cvt_f32_f16_e32 v24, v25
	v_cvt_f32_f16_sdwa v25, v25 dst_sel:DWORD dst_unused:UNUSED_PAD src0_sel:WORD_1
	v_pk_mul_f32 v[20:21], v[20:21], v[28:29]
	s_nop 0
	v_cvt_pk_f16_f32 v20, v20, v21
	v_pk_mul_f32 v[22:23], v[22:23], v[24:25]
	s_nop 0
	v_cvt_pk_f16_f32 v21, v22, v23
	v_cvt_f32_f16_e32 v22, v26
	v_cvt_f32_f16_sdwa v23, v26 dst_sel:DWORD dst_unused:UNUSED_PAD src0_sel:WORD_1
	v_pk_mul_f32 v[16:17], v[16:17], v[22:23]
	s_nop 0
	v_cvt_pk_f16_f32 v22, v16, v17
	v_pk_mul_f32 v[16:17], v[18:19], v[36:37] op_sel_hi:[1,0]
	v_cvt_f32_f16_e32 v18, v27
	v_cvt_f32_f16_sdwa v19, v27 dst_sel:DWORD dst_unused:UNUSED_PAD src0_sel:WORD_1
	v_pk_mul_f32 v[16:17], v[16:17], v[18:19]
	s_nop 0
	v_cvt_pk_f16_f32 v23, v16, v17
	global_store_dwordx4 v[38:39], v[20:23], off offset:16
	global_load_dwordx4 v[16:19], v[42:43], off offset:32
	s_waitcnt vmcnt(0)
	v_cvt_f32_f16_e32 v20, v16
	v_cvt_f32_f16_sdwa v21, v16 dst_sel:DWORD dst_unused:UNUSED_PAD src0_sel:WORD_1
	v_cvt_f32_f16_e32 v16, v17
	v_cvt_f32_f16_sdwa v17, v17 dst_sel:DWORD dst_unused:UNUSED_PAD src0_sel:WORD_1
	v_pk_mul_f32 v[12:13], v[12:13], v[20:21]
	s_nop 0
	v_cvt_pk_f16_f32 v12, v12, v13
	v_pk_mul_f32 v[14:15], v[14:15], v[16:17]
	s_nop 0
	v_cvt_pk_f16_f32 v13, v14, v15
	v_cvt_f32_f16_e32 v14, v18
	v_cvt_f32_f16_sdwa v15, v18 dst_sel:DWORD dst_unused:UNUSED_PAD src0_sel:WORD_1
	v_pk_mul_f32 v[8:9], v[8:9], v[14:15]
	s_nop 0
	v_cvt_pk_f16_f32 v14, v8, v9
	v_pk_mul_f32 v[8:9], v[10:11], v[36:37] op_sel_hi:[1,0]
	v_cvt_f32_f16_e32 v10, v19
	v_cvt_f32_f16_sdwa v11, v19 dst_sel:DWORD dst_unused:UNUSED_PAD src0_sel:WORD_1
	v_pk_mul_f32 v[8:9], v[8:9], v[10:11]
	s_nop 0
	v_cvt_pk_f16_f32 v15, v8, v9
	global_store_dwordx4 v[38:39], v[12:15], off offset:32
	global_load_dwordx4 v[8:11], v[42:43], off offset:48
	s_waitcnt vmcnt(0)
	v_cvt_f32_f16_e32 v12, v8
	v_cvt_f32_f16_sdwa v13, v8 dst_sel:DWORD dst_unused:UNUSED_PAD src0_sel:WORD_1
	v_cvt_f32_f16_e32 v8, v9
	v_cvt_f32_f16_sdwa v9, v9 dst_sel:DWORD dst_unused:UNUSED_PAD src0_sel:WORD_1
	v_pk_mul_f32 v[4:5], v[4:5], v[12:13]
	s_nop 0
	v_cvt_pk_f16_f32 v4, v4, v5
	v_pk_mul_f32 v[6:7], v[6:7], v[8:9]
	s_nop 0
	v_cvt_pk_f16_f32 v5, v6, v7
	v_cvt_f32_f16_e32 v6, v10
	v_cvt_f32_f16_sdwa v7, v10 dst_sel:DWORD dst_unused:UNUSED_PAD src0_sel:WORD_1
	v_pk_mul_f32 v[0:1], v[0:1], v[6:7]
	s_nop 0
	v_cvt_pk_f16_f32 v6, v0, v1
	v_pk_mul_f32 v[0:1], v[2:3], v[36:37] op_sel_hi:[1,0]
	v_cvt_f32_f16_e32 v2, v11
	v_cvt_f32_f16_sdwa v3, v11 dst_sel:DWORD dst_unused:UNUSED_PAD src0_sel:WORD_1
	v_pk_mul_f32 v[0:1], v[0:1], v[2:3]
	s_nop 0
	v_cvt_pk_f16_f32 v7, v0, v1
	global_store_dwordx4 v[38:39], v[4:7], off offset:48
	s_cbranch_scc1 .LBB0_84
.LBB0_76:
	s_bfe_u32 s18, s4, 0x10008
	s_lshl_b32 s18, s18, 2
	s_xor_b32 s4, s4, s18
	s_and_b32 s18, s4, 7
	s_ashr_i32 s2, s4, 3
	s_lshl_b32 s7, s18, 6
	s_lshl_b32 s16, s2, 6
	s_add_i32 s3, s7, 0xb40
	s_or_b32 s5, s7, 0x100
	s_add_i32 s6, s7, 0xc40
	s_lshl_b32 s17, s18, 7
	s_cmp_lt_u32 s18, 4
	s_cselect_b64 s[8:9], -1, 0
	s_and_b64 s[10:11], s[8:9], exec
	s_cselect_b32 s5, s5, s6
	s_movk_i32 s6, 0xc40
	s_cselect_b32 s6, 0x200, s6
	s_waitcnt vmcnt(11)
	v_mbcnt_lo_u32_b32 v66, -1, 0
	v_mbcnt_hi_u32_b32 v66, -1, v66
	v_readlane_b32 s19, v253, 22
	s_cselect_b32 s3, s7, s3
	s_or_b32 s6, s6, s17
	s_lshl_b32 s20, s5, 1
	s_ashr_i32 s5, s4, 31
	v_mbcnt_lo_u32_b32 v0, -1, 0
	v_mbcnt_hi_u32_b32 v0, -1, v0
	v_or_b32_e32 v67, s19, v66
	v_or_b32_e32 v1, s55, v0
	s_lshl_b32 s90, s6, 1
	s_lshl_b32 s10, s3, 1
	s_lshl_b64 s[22:23], s[4:5], 14
	v_readlane_b32 s24, v253, 47
	v_bfe_u32 v2, v0, 5, 1
	v_ashrrev_i32_e32 v1, 5, v1
	s_mov_b32 s3, 0x1ffffffe
	v_lshlrev_b32_e32 v0, 1, v0
	v_readlane_b32 s25, v253, 48
	s_add_u32 s22, s24, s22
	v_and_or_b32 v4, v1, s3, v2
	v_and_or_b32 v2, v0, 62, s16
	s_waitcnt vmcnt(0)
	v_mov_b64_e32 v[16:17], s[56:57]
	s_waitcnt vmcnt(54)
	v_ashrrev_i32_e32 v70, 3, v67
	s_addc_u32 s23, s25, s23
	v_mad_i64_i32 v[0:1], s[24:25], v2, s68, v[16:17]
	v_or_b32_e32 v2, 1, v2
	v_lshlrev_b32_e32 v4, 3, v4
	v_lshlrev_b32_e32 v22, 3, v67
	v_add_u32_e32 v18, s16, v70
	v_mad_i64_i32 v[2:3], s[24:25], v2, s68, v[16:17]
	v_ashrrev_i32_e32 v5, 31, v4
	v_and_b32_e32 v68, 56, v22
	v_mad_i64_i32 v[18:19], s[24:25], v18, s68, v[16:17]
	s_mov_b32 s11, s91
	s_mov_b32 s21, s91
	v_lshl_add_u64 v[0:1], v[0:1], 0, s[90:91]
	v_lshl_add_u64 v[2:3], v[2:3], 0, s[90:91]
	v_lshlrev_b64 v[4:5], 1, v[4:5]
	v_lshl_add_u64 v[20:21], v[18:19], 0, s[10:11]
	v_lshlrev_b32_e32 v40, 1, v68
	v_lshl_add_u64 v[18:19], v[18:19], 0, s[20:21]
	v_lshl_add_u64 v[0:1], v[0:1], 0, v[4:5]
	v_lshl_add_u64 v[4:5], v[2:3], 0, v[4:5]
	v_lshl_add_u64 v[20:21], v[20:21], 0, v[40:41]
	v_lshl_add_u64 v[18:19], v[18:19], 0, v[40:41]
	global_load_dwordx4 v[8:11], v[0:1], off
	s_nop 0
	global_load_dwordx4 v[0:3], v[0:1], off offset:128
	s_nop 0
	global_load_dwordx4 v[12:15], v[4:5], off
	s_nop 0
	global_load_dwordx4 v[4:7], v[4:5], off offset:128
	s_nop 0
	global_load_dwordx4 v[44:47], v[20:21], off
	global_load_dwordx4 v[48:51], v[18:19], off
	v_add_u32_e32 v18, 0x100, v67
	v_ashrrev_i32_e32 v69, 3, v18
	v_add_u32_e32 v18, s16, v69
	v_mad_i64_i32 v[16:17], s[24:25], v18, s68, v[16:17]
	v_lshl_add_u64 v[18:19], v[16:17], 0, s[10:11]
	v_lshl_add_u64 v[16:17], v[16:17], 0, s[20:21]
	v_and_b32_e32 v26, 0xffffffc0, v22
	v_lshl_add_u64 v[18:19], v[18:19], 0, v[40:41]
	v_lshl_add_u64 v[16:17], v[16:17], 0, v[40:41]
	v_lshl_add_u64 v[24:25], s[22:23], 0, v[40:41]
	v_ashrrev_i32_e32 v27, 31, v26
	global_load_dwordx4 v[36:39], v[18:19], off
	global_load_dwordx4 v[32:35], v[16:17], off
	v_lshl_add_u64 v[16:17], v[26:27], 1, v[24:25]
	v_add_u32_e32 v18, 0x800, v26
	v_add_u32_e32 v28, 0x1000, v26
	v_add_u32_e32 v26, 0x1800, v26
	v_ashrrev_i32_e32 v19, 31, v18
	v_ashrrev_i32_e32 v29, 31, v28
	v_ashrrev_i32_e32 v27, 31, v26
	v_lshl_add_u64 v[18:19], v[18:19], 1, v[24:25]
	v_lshl_add_u64 v[28:29], v[28:29], 1, v[24:25]
	v_lshl_add_u64 v[24:25], v[26:27], 1, v[24:25]
	global_load_dwordx4 v[20:23], v[16:17], off
	s_nop 0
	global_load_dwordx4 v[16:19], v[18:19], off
	s_nop 0
	global_load_dwordx4 v[28:31], v[28:29], off
	s_nop 0
	global_load_dwordx4 v[24:27], v[24:25], off
	s_waitcnt vmcnt(63) expcnt(7) lgkmcnt(15)
	s_barrier
	v_mbcnt_lo_u32_b32 v40, -1, 0
	v_mbcnt_hi_u32_b32 v40, -1, v40
	s_cmp_gt_u32 s18, 3
	v_or_b32_e32 v42, s19, v40
	v_and_b32_e32 v40, 63, v40
	v_ashrrev_i32_e32 v71, 6, v42
	s_mov_b64 s[10:11], -1
	s_cbranch_scc0 .LBB0_82
	s_ashr_i32 s3, s2, 31
	s_lshl_b64 s[2:3], s[2:3], 12
	v_readlane_b32 s5, v254, 17
	s_add_u32 s2, s5, s2
	v_readlane_b32 s5, v254, 18
	s_addc_u32 s3, s5, s3
	s_add_i32 s90, s7, 0xffffff00
	s_lshl_b64 s[10:11], s[90:91], 2
	s_add_u32 s10, s12, s10
	s_addc_u32 s11, s13, s11
	v_lshlrev_b32_e32 v52, 2, v40
	v_mov_b32_e32 v53, v41
	v_ashrrev_i32_e32 v43, 31, v42
	v_lshl_add_u64 v[54:55], s[10:11], 0, v[52:53]
	v_lshl_add_u64 v[56:57], v[42:43], 2, s[2:3]
	v_lshlrev_b32_e32 v53, 2, v42
	v_add_u32_e32 v58, 0x400, v53
	v_add_u32_e32 v60, 0x800, v53
	global_load_dword v62, v[56:57], off
	global_load_dword v63, v[56:57], off offset:1024
	global_load_dword v64, v[56:57], off offset:2048
	global_load_dword v65, v[56:57], off offset:3072
	v_add_u32_e32 v56, 0xc00, v53
	v_and_b32_e32 v42, 0xffffff00, v53
	v_and_b32_e32 v58, 0xffffff00, v58
	v_and_b32_e32 v60, 0xffffff00, v60
	v_and_b32_e32 v56, 0xffffff00, v56
	v_ashrrev_i32_e32 v43, 31, v42
	v_ashrrev_i32_e32 v59, 31, v58
	v_ashrrev_i32_e32 v61, 31, v60
	v_ashrrev_i32_e32 v57, 31, v56
	v_lshl_add_u64 v[42:43], v[42:43], 2, v[54:55]
	v_lshl_add_u64 v[58:59], v[58:59], 2, v[54:55]
	v_lshl_add_u64 v[60:61], v[60:61], 2, v[54:55]
	v_lshl_add_u64 v[54:55], v[56:57], 2, v[54:55]
	global_load_dword v56, v[42:43], off
	global_load_dword v57, v[58:59], off
	s_nop 0
	global_load_dword v58, v[60:61], off
	s_nop 0
	global_load_dword v54, v[54:55], off
	s_add_u32 s2, s7, s14
	s_addc_u32 s3, 0, s15
	v_readlane_b32 s36, v253, 6
	v_lshl_add_u64 v[42:43], v[40:41], 0, s[2:3]
	v_readlane_b32 s38, v253, 8
	v_readlane_b32 s39, v253, 9
	v_add_u32_e32 v72, 0, v53
	v_add_u32_e32 v78, 0, v52
	v_lshl_add_u64 v[42:43], v[42:43], 2, s[38:39]
	v_lshl_add_u32 v76, v71, 10, 0
	s_mov_b32 s2, 0xbfb8aa3b
	s_movk_i32 s3, 0x1040
	v_mul_lo_u32 v77, v71, s3
	s_mov_b32 s3, 0x3f317217
	v_mov_b32_e32 v100, 0x41b17218
	s_mov_b32 s5, 0x7f800000
	s_mov_b32 s6, 0x3d800000
	v_lshl_or_b32 v79, v71, 4, 1
	v_readlane_b32 s37, v253, 7
	v_readlane_b32 s40, v253, 10
	v_readlane_b32 s41, v253, 11
	v_readlane_b32 s42, v253, 12
	v_readlane_b32 s43, v253, 13
	v_readlane_b32 s44, v253, 14
	v_readlane_b32 s45, v253, 15
	v_readlane_b32 s46, v253, 16
	v_readlane_b32 s47, v253, 17
	v_readlane_b32 s48, v253, 18
	v_readlane_b32 s49, v253, 19
	v_readlane_b32 s50, v253, 20
	v_readlane_b32 s51, v253, 21
	s_waitcnt vmcnt(6)
	ds_write2st64_b32 v72, v62, v63 offset0:65 offset1:69
	s_waitcnt vmcnt(4)
	ds_write2st64_b32 v72, v64, v65 offset0:73 offset1:77
	s_waitcnt vmcnt(2)
	ds_write2st64_b32 v72, v56, v57 offset0:81 offset1:85
	s_waitcnt vmcnt(0)
	ds_write2st64_b32 v72, v58, v54 offset0:89 offset1:93
	s_waitcnt lgkmcnt(0)
	s_barrier
	global_load_dword v73, v[42:43], off offset:-1024
	ds_read2st64_b32 v[64:65], v78 offset0:81 offset1:82
	ds_read2st64_b32 v[62:63], v78 offset0:83 offset1:84
	ds_read2st64_b32 v[60:61], v78 offset0:85 offset1:86
	ds_read2st64_b32 v[58:59], v78 offset0:87 offset1:88
	ds_read_b128 v[84:87], v76 offset:16640
	ds_read2st64_b32 v[56:57], v78 offset0:89 offset1:90
	ds_read2st64_b32 v[54:55], v78 offset0:91 offset1:92
	ds_read2st64_b32 v[52:53], v78 offset0:93 offset1:94
	ds_read2st64_b32 v[42:43], v78 offset0:95 offset1:96
	ds_read_b128 v[88:91], v76 offset:16656
	ds_read_b128 v[92:95], v76 offset:16672
	ds_read_b128 v[96:99], v76 offset:16688
	s_waitcnt vmcnt(0) lgkmcnt(7)
	v_fma_f32 v75, v64, v84, v73
	v_fmac_f32_e32 v75, v65, v85
	v_fmac_f32_e32 v75, v62, v86
	v_fmac_f32_e32 v75, v63, v87
	s_waitcnt lgkmcnt(2)
	v_fmac_f32_e32 v75, v60, v88
	v_fmac_f32_e32 v75, v61, v89
	v_fmac_f32_e32 v75, v58, v90
	v_fmac_f32_e32 v75, v59, v91
	s_waitcnt lgkmcnt(1)
	v_fmac_f32_e32 v75, v56, v92
	v_fmac_f32_e32 v75, v57, v93
	v_fmac_f32_e32 v75, v54, v94
	v_fmac_f32_e32 v75, v55, v95
	s_waitcnt lgkmcnt(0)
	v_fmac_f32_e32 v75, v52, v96
	v_fmac_f32_e32 v75, v53, v97
	v_fmac_f32_e32 v75, v42, v98
	v_fmac_f32_e32 v75, v43, v99
	v_mul_f32_e64 v74, |v75|, s2
	v_exp_f32_e32 v74, v74
	v_min_f32_e32 v75, 0, v75
	v_lshl_add_u32 v96, v79, 6, 0
	v_add_f32_e32 v74, 1.0, v74
	v_cmp_gt_f32_e32 vcc, s70, v74
	s_nop 1
	v_cndmask_b32_e64 v84, 0, 32, vcc
	v_ldexp_f32 v74, v74, v84
	v_log_f32_e32 v84, v74
	v_add_u32_e32 v74, v78, v77
	v_cndmask_b32_e32 v77, 0, v100, vcc
	v_mul_f32_e32 v85, 0x3f317217, v84
	v_fma_f32 v85, v84, s3, -v85
	v_fmac_f32_e32 v85, 0x3377d1cf, v84
	v_fmac_f32_e32 v85, 0x3f317217, v84
	v_cmp_lt_f32_e64 vcc, |v84|, s5
	s_nop 1
	v_cndmask_b32_e32 v84, v84, v85, vcc
	v_sub_f32_e32 v77, v84, v77
	v_sub_f32_e32 v75, v75, v77
	v_fma_f32 v77, v75, s6, 0
	ds_write_b32 v74, v77
	ds_read_b128 v[84:87], v96 offset:16640
	ds_read_b128 v[88:91], v96 offset:16656
	ds_read_b128 v[92:95], v96 offset:16672
	ds_read_b128 v[96:99], v96 offset:16688
	s_movk_i32 s6, 0x104
	s_waitcnt lgkmcnt(3)
	v_fma_f32 v84, v64, v84, v73
	v_fmac_f32_e32 v84, v65, v85
	v_fmac_f32_e32 v84, v62, v86
	v_fmac_f32_e32 v84, v63, v87
	s_waitcnt lgkmcnt(2)
	v_fmac_f32_e32 v84, v60, v88
	v_fmac_f32_e32 v84, v61, v89
	v_fmac_f32_e32 v84, v58, v90
	v_fmac_f32_e32 v84, v59, v91
	s_waitcnt lgkmcnt(1)
	v_fmac_f32_e32 v84, v56, v92
	v_fmac_f32_e32 v84, v57, v93
	v_fmac_f32_e32 v84, v54, v94
	v_fmac_f32_e32 v84, v55, v95
	s_waitcnt lgkmcnt(0)
	v_fmac_f32_e32 v84, v52, v96
	v_fmac_f32_e32 v84, v53, v97
	v_fmac_f32_e32 v84, v42, v98
	v_fmac_f32_e32 v84, v43, v99
	v_mul_f32_e64 v75, |v84|, s2
	v_exp_f32_e32 v75, v75
	v_min_f32_e32 v84, 0, v84
	v_mul_lo_u32 v79, v79, s6
	v_add_f32_e32 v75, 1.0, v75
	v_cmp_gt_f32_e32 vcc, s70, v75
	s_nop 1
	v_cndmask_b32_e64 v85, 0, 32, vcc
	v_ldexp_f32 v75, v75, v85
	v_log_f32_e32 v85, v75
	v_cndmask_b32_e32 v86, 0, v100, vcc
	v_add_u32_e32 v75, v78, v79
	v_add_u32_e32 v79, 0x618, v79
	v_mul_f32_e32 v87, 0x3f317217, v85
	v_fma_f32 v87, v85, s3, -v87
	v_fmac_f32_e32 v87, 0x3377d1cf, v85
	v_fmac_f32_e32 v87, 0x3f317217, v85
	v_cmp_lt_f32_e64 vcc, |v85|, s5
	v_add_u32_e32 v78, v78, v79
	s_nop 0
	v_cndmask_b32_e32 v85, v85, v87, vcc
	v_sub_f32_e32 v85, v85, v86
	v_sub_f32_e32 v84, v84, v85
	v_fmac_f32_e32 v77, 0x3d800000, v84
	ds_write_b32 v75, v77
	ds_read_b128 v[84:87], v76 offset:16768
	ds_read_b128 v[88:91], v76 offset:16784
	ds_read_b128 v[92:95], v76 offset:16800
	ds_read_b128 v[96:99], v76 offset:16816
	s_waitcnt lgkmcnt(3)
	v_fma_f32 v84, v64, v84, v73
	v_fmac_f32_e32 v84, v65, v85
	v_fmac_f32_e32 v84, v62, v86
	v_fmac_f32_e32 v84, v63, v87
	s_waitcnt lgkmcnt(2)
	v_fmac_f32_e32 v84, v60, v88
	v_fmac_f32_e32 v84, v61, v89
	v_fmac_f32_e32 v84, v58, v90
	v_fmac_f32_e32 v84, v59, v91
	s_waitcnt lgkmcnt(1)
	v_fmac_f32_e32 v84, v56, v92
	v_fmac_f32_e32 v84, v57, v93
	v_fmac_f32_e32 v84, v54, v94
	v_fmac_f32_e32 v84, v55, v95
	s_waitcnt lgkmcnt(0)
	v_fmac_f32_e32 v84, v52, v96
	v_fmac_f32_e32 v84, v53, v97
	v_fmac_f32_e32 v84, v42, v98
	v_fmac_f32_e32 v84, v43, v99
	v_mul_f32_e64 v85, |v84|, s2
	v_exp_f32_e32 v85, v85
	v_min_f32_e32 v84, 0, v84
	v_add_f32_e32 v85, 1.0, v85
	v_cmp_gt_f32_e32 vcc, s70, v85
	s_nop 1
	v_cndmask_b32_e64 v86, 0, 32, vcc
	v_ldexp_f32 v85, v85, v86
	v_log_f32_e32 v85, v85
	v_cndmask_b32_e32 v86, 0, v100, vcc
	v_mul_f32_e32 v87, 0x3f317217, v85
	v_fma_f32 v87, v85, s3, -v87
	v_fmac_f32_e32 v87, 0x3377d1cf, v85
	v_fmac_f32_e32 v87, 0x3f317217, v85
	v_cmp_lt_f32_e64 vcc, |v85|, s5
	s_nop 1
	v_cndmask_b32_e32 v85, v85, v87, vcc
	v_sub_f32_e32 v85, v85, v86
	v_sub_f32_e32 v84, v84, v85
	v_fmac_f32_e32 v77, 0x3d800000, v84
	ds_write_b32 v75, v77 offset:260
	ds_read_b128 v[84:87], v76 offset:16832
	ds_read_b128 v[88:91], v76 offset:16848
	ds_read_b128 v[92:95], v76 offset:16864
	ds_read_b128 v[96:99], v76 offset:16880
	s_waitcnt lgkmcnt(3)
	v_fma_f32 v84, v64, v84, v73
	v_fmac_f32_e32 v84, v65, v85
	v_fmac_f32_e32 v84, v62, v86
	v_fmac_f32_e32 v84, v63, v87
	s_waitcnt lgkmcnt(2)
	v_fmac_f32_e32 v84, v60, v88
	v_fmac_f32_e32 v84, v61, v89
	v_fmac_f32_e32 v84, v58, v90
	v_fmac_f32_e32 v84, v59, v91
	s_waitcnt lgkmcnt(1)
	v_fmac_f32_e32 v84, v56, v92
	v_fmac_f32_e32 v84, v57, v93
	v_fmac_f32_e32 v84, v54, v94
	v_fmac_f32_e32 v84, v55, v95
	s_waitcnt lgkmcnt(0)
	v_fmac_f32_e32 v84, v52, v96
	v_fmac_f32_e32 v84, v53, v97
	v_fmac_f32_e32 v84, v42, v98
	v_fmac_f32_e32 v84, v43, v99
	v_mul_f32_e64 v85, |v84|, s2
	v_exp_f32_e32 v85, v85
	v_min_f32_e32 v84, 0, v84
	v_add_f32_e32 v85, 1.0, v85
	v_cmp_gt_f32_e32 vcc, s70, v85
	s_nop 1
	v_cndmask_b32_e64 v86, 0, 32, vcc
	v_ldexp_f32 v85, v85, v86
	v_log_f32_e32 v85, v85
	v_cndmask_b32_e32 v86, 0, v100, vcc
	v_mul_f32_e32 v87, 0x3f317217, v85
	v_fma_f32 v87, v85, s3, -v87
	v_fmac_f32_e32 v87, 0x3377d1cf, v85
	v_fmac_f32_e32 v87, 0x3f317217, v85
	v_cmp_lt_f32_e64 vcc, |v85|, s5
	s_nop 1
	v_cndmask_b32_e32 v85, v85, v87, vcc
	v_sub_f32_e32 v85, v85, v86
	v_sub_f32_e32 v84, v84, v85
	v_fmac_f32_e32 v77, 0x3d800000, v84
	ds_write_b32 v75, v77 offset:520
	ds_read_b128 v[84:87], v76 offset:16896
	ds_read_b128 v[88:91], v76 offset:16912
	ds_read_b128 v[92:95], v76 offset:16928
	ds_read_b128 v[96:99], v76 offset:16944
	s_waitcnt lgkmcnt(3)
	v_fma_f32 v84, v64, v84, v73
	v_fmac_f32_e32 v84, v65, v85
	v_fmac_f32_e32 v84, v62, v86
	v_fmac_f32_e32 v84, v63, v87
	s_waitcnt lgkmcnt(2)
	v_fmac_f32_e32 v84, v60, v88
	v_fmac_f32_e32 v84, v61, v89
	v_fmac_f32_e32 v84, v58, v90
	v_fmac_f32_e32 v84, v59, v91
	s_waitcnt lgkmcnt(1)
	v_fmac_f32_e32 v84, v56, v92
	v_fmac_f32_e32 v84, v57, v93
	v_fmac_f32_e32 v84, v54, v94
	v_fmac_f32_e32 v84, v55, v95
	s_waitcnt lgkmcnt(0)
	v_fmac_f32_e32 v84, v52, v96
	v_fmac_f32_e32 v84, v53, v97
	v_fmac_f32_e32 v84, v42, v98
	v_fmac_f32_e32 v84, v43, v99
	v_mul_f32_e64 v85, |v84|, s2
	v_exp_f32_e32 v85, v85
	v_min_f32_e32 v84, 0, v84
	v_add_f32_e32 v85, 1.0, v85
	v_cmp_gt_f32_e32 vcc, s70, v85
	s_nop 1
	v_cndmask_b32_e64 v86, 0, 32, vcc
	v_ldexp_f32 v85, v85, v86
	v_log_f32_e32 v85, v85
	v_cndmask_b32_e32 v86, 0, v100, vcc
	v_mul_f32_e32 v87, 0x3f317217, v85
	v_fma_f32 v87, v85, s3, -v87
	v_fmac_f32_e32 v87, 0x3377d1cf, v85
	v_fmac_f32_e32 v87, 0x3f317217, v85
	v_cmp_lt_f32_e64 vcc, |v85|, s5
	s_nop 1
	v_cndmask_b32_e32 v85, v85, v87, vcc
	v_sub_f32_e32 v85, v85, v86
	v_sub_f32_e32 v84, v84, v85
	v_fmac_f32_e32 v77, 0x3d800000, v84
	ds_write_b32 v75, v77 offset:780
	ds_read_b128 v[84:87], v76 offset:16960
	ds_read_b128 v[88:91], v76 offset:16976
	ds_read_b128 v[92:95], v76 offset:16992
	ds_read_b128 v[96:99], v76 offset:17008
	s_waitcnt lgkmcnt(3)
	v_fma_f32 v84, v64, v84, v73
	v_fmac_f32_e32 v84, v65, v85
	v_fmac_f32_e32 v84, v62, v86
	v_fmac_f32_e32 v84, v63, v87
	s_waitcnt lgkmcnt(2)
	v_fmac_f32_e32 v84, v60, v88
	v_fmac_f32_e32 v84, v61, v89
	v_fmac_f32_e32 v84, v58, v90
	v_fmac_f32_e32 v84, v59, v91
	s_waitcnt lgkmcnt(1)
	v_fmac_f32_e32 v84, v56, v92
	v_fmac_f32_e32 v84, v57, v93
	v_fmac_f32_e32 v84, v54, v94
	v_fmac_f32_e32 v84, v55, v95
	s_waitcnt lgkmcnt(0)
	v_fmac_f32_e32 v84, v52, v96
	v_fmac_f32_e32 v84, v53, v97
	v_fmac_f32_e32 v84, v42, v98
	v_fmac_f32_e32 v84, v43, v99
	v_mul_f32_e64 v85, |v84|, s2
	v_exp_f32_e32 v85, v85
	v_min_f32_e32 v84, 0, v84
	v_add_f32_e32 v85, 1.0, v85
	v_cmp_gt_f32_e32 vcc, s70, v85
	s_nop 1
	v_cndmask_b32_e64 v86, 0, 32, vcc
	v_ldexp_f32 v85, v85, v86
	v_log_f32_e32 v85, v85
	v_cndmask_b32_e32 v86, 0, v100, vcc
	v_mul_f32_e32 v87, 0x3f317217, v85
	v_fma_f32 v87, v85, s3, -v87
	v_fmac_f32_e32 v87, 0x3377d1cf, v85
	v_fmac_f32_e32 v87, 0x3f317217, v85
	v_cmp_lt_f32_e64 vcc, |v85|, s5
	s_nop 1
	v_cndmask_b32_e32 v85, v85, v87, vcc
	v_sub_f32_e32 v85, v85, v86
	v_sub_f32_e32 v84, v84, v85
	v_fmac_f32_e32 v77, 0x3d800000, v84
	ds_write_b32 v75, v77 offset:1040
	ds_read_b128 v[84:87], v76 offset:17024
	ds_read_b128 v[88:91], v76 offset:17040
	ds_read_b128 v[92:95], v76 offset:17056
	ds_read_b128 v[96:99], v76 offset:17072
	s_waitcnt lgkmcnt(3)
	v_fma_f32 v84, v64, v84, v73
	v_fmac_f32_e32 v84, v65, v85
	v_fmac_f32_e32 v84, v62, v86
	v_fmac_f32_e32 v84, v63, v87
	s_waitcnt lgkmcnt(2)
	v_fmac_f32_e32 v84, v60, v88
	v_fmac_f32_e32 v84, v61, v89
	v_fmac_f32_e32 v84, v58, v90
	v_fmac_f32_e32 v84, v59, v91
	s_waitcnt lgkmcnt(1)
	v_fmac_f32_e32 v84, v56, v92
	v_fmac_f32_e32 v84, v57, v93
	v_fmac_f32_e32 v84, v54, v94
	v_fmac_f32_e32 v84, v55, v95
	s_waitcnt lgkmcnt(0)
	v_fmac_f32_e32 v84, v52, v96
	v_fmac_f32_e32 v84, v53, v97
	v_fmac_f32_e32 v84, v42, v98
	v_fmac_f32_e32 v84, v43, v99
	v_mul_f32_e64 v85, |v84|, s2
	v_exp_f32_e32 v85, v85
	v_min_f32_e32 v84, 0, v84
	v_add_f32_e32 v85, 1.0, v85
	v_cmp_gt_f32_e32 vcc, s70, v85
	s_nop 1
	v_cndmask_b32_e64 v86, 0, 32, vcc
	v_ldexp_f32 v85, v85, v86
	v_log_f32_e32 v85, v85
	v_cndmask_b32_e32 v86, 0, v100, vcc
	v_mul_f32_e32 v87, 0x3f317217, v85
	v_fma_f32 v87, v85, s3, -v87
	v_fmac_f32_e32 v87, 0x3377d1cf, v85
	v_fmac_f32_e32 v87, 0x3f317217, v85
	v_cmp_lt_f32_e64 vcc, |v85|, s5
	s_nop 1
	v_cndmask_b32_e32 v85, v85, v87, vcc
	v_sub_f32_e32 v85, v85, v86
	v_sub_f32_e32 v84, v84, v85
	v_fmac_f32_e32 v77, 0x3d800000, v84
	ds_write_b32 v75, v77 offset:1300
	ds_read_b128 v[84:87], v76 offset:17088
	ds_read_b128 v[88:91], v76 offset:17104
	ds_read_b128 v[92:95], v76 offset:17120
	ds_read_b128 v[96:99], v76 offset:17136
	s_waitcnt lgkmcnt(3)
	v_fma_f32 v84, v64, v84, v73
	v_fmac_f32_e32 v84, v65, v85
	v_fmac_f32_e32 v84, v62, v86
	v_fmac_f32_e32 v84, v63, v87
	s_waitcnt lgkmcnt(2)
	v_fmac_f32_e32 v84, v60, v88
	v_fmac_f32_e32 v84, v61, v89
	v_fmac_f32_e32 v84, v58, v90
	v_fmac_f32_e32 v84, v59, v91
	s_waitcnt lgkmcnt(1)
	v_fmac_f32_e32 v84, v56, v92
	v_fmac_f32_e32 v84, v57, v93
	v_fmac_f32_e32 v84, v54, v94
	v_fmac_f32_e32 v84, v55, v95
	s_waitcnt lgkmcnt(0)
	v_fmac_f32_e32 v84, v52, v96
	v_fmac_f32_e32 v84, v53, v97
	v_fmac_f32_e32 v84, v42, v98
	v_fmac_f32_e32 v84, v43, v99
	v_mul_f32_e64 v85, |v84|, s2
	v_exp_f32_e32 v85, v85
	v_min_f32_e32 v79, 0, v84
	v_add_f32_e32 v85, 1.0, v85
	v_cmp_gt_f32_e32 vcc, s70, v85
	s_nop 1
	v_cndmask_b32_e64 v86, 0, 32, vcc
	v_ldexp_f32 v85, v85, v86
	v_log_f32_e32 v85, v85
	v_cndmask_b32_e32 v84, 0, v100, vcc
	v_mul_f32_e32 v86, 0x3f317217, v85
	v_fma_f32 v86, v85, s3, -v86
	v_fmac_f32_e32 v86, 0x3377d1cf, v85
	v_fmac_f32_e32 v86, 0x3f317217, v85
	v_cmp_lt_f32_e64 vcc, |v85|, s5
	s_nop 1
	v_cndmask_b32_e32 v85, v85, v86, vcc
	v_sub_f32_e32 v84, v85, v84
	v_sub_f32_e32 v79, v79, v84
	v_fmac_f32_e32 v77, 0x3d800000, v79
	ds_write_b32 v78, v77
	ds_read_b128 v[84:87], v76 offset:17152
	ds_read_b128 v[88:91], v76 offset:17168
	ds_read_b128 v[92:95], v76 offset:17184
	ds_read_b128 v[96:99], v76 offset:17200
	s_waitcnt lgkmcnt(3)
	v_fma_f32 v79, v64, v84, v73
	v_fmac_f32_e32 v79, v65, v85
	v_fmac_f32_e32 v79, v62, v86
	v_fmac_f32_e32 v79, v63, v87
	s_waitcnt lgkmcnt(2)
	v_fmac_f32_e32 v79, v60, v88
	v_fmac_f32_e32 v79, v61, v89
	v_fmac_f32_e32 v79, v58, v90
	v_fmac_f32_e32 v79, v59, v91
	s_waitcnt lgkmcnt(1)
	v_fmac_f32_e32 v79, v56, v92
	v_fmac_f32_e32 v79, v57, v93
	v_fmac_f32_e32 v79, v54, v94
	v_fmac_f32_e32 v79, v55, v95
	s_waitcnt lgkmcnt(0)
	v_fmac_f32_e32 v79, v52, v96
	v_fmac_f32_e32 v79, v53, v97
	v_fmac_f32_e32 v79, v42, v98
	v_fmac_f32_e32 v79, v43, v99
	v_mul_f32_e64 v84, |v79|, s2
	v_exp_f32_e32 v84, v84
	v_min_f32_e32 v79, 0, v79
	v_add_f32_e32 v84, 1.0, v84
	v_cmp_gt_f32_e32 vcc, s70, v84
	s_nop 1
	v_cndmask_b32_e64 v85, 0, 32, vcc
	v_ldexp_f32 v84, v84, v85
	v_log_f32_e32 v84, v84
	v_cndmask_b32_e32 v85, 0, v100, vcc
	v_mul_f32_e32 v86, 0x3f317217, v84
	v_fma_f32 v86, v84, s3, -v86
	v_fmac_f32_e32 v86, 0x3377d1cf, v84
	v_fmac_f32_e32 v86, 0x3f317217, v84
	v_cmp_lt_f32_e64 vcc, |v84|, s5
	s_nop 1
	v_cndmask_b32_e32 v84, v84, v86, vcc
	v_sub_f32_e32 v84, v84, v85
	v_sub_f32_e32 v79, v79, v84
	v_fmac_f32_e32 v77, 0x3d800000, v79
	ds_write_b32 v78, v77 offset:260
	ds_read_b128 v[84:87], v76 offset:17216
	ds_read_b128 v[88:91], v76 offset:17232
	ds_read_b128 v[92:95], v76 offset:17248
	ds_read_b128 v[96:99], v76 offset:17264
	s_waitcnt lgkmcnt(3)
	v_fma_f32 v79, v64, v84, v73
	v_fmac_f32_e32 v79, v65, v85
	v_fmac_f32_e32 v79, v62, v86
	v_fmac_f32_e32 v79, v63, v87
	s_waitcnt lgkmcnt(2)
	v_fmac_f32_e32 v79, v60, v88
	v_fmac_f32_e32 v79, v61, v89
	v_fmac_f32_e32 v79, v58, v90
	v_fmac_f32_e32 v79, v59, v91
	s_waitcnt lgkmcnt(1)
	v_fmac_f32_e32 v79, v56, v92
	v_fmac_f32_e32 v79, v57, v93
	v_fmac_f32_e32 v79, v54, v94
	v_fmac_f32_e32 v79, v55, v95
	s_waitcnt lgkmcnt(0)
	v_fmac_f32_e32 v79, v52, v96
	v_fmac_f32_e32 v79, v53, v97
	v_fmac_f32_e32 v79, v42, v98
	v_fmac_f32_e32 v79, v43, v99
	v_mul_f32_e64 v84, |v79|, s2
	v_exp_f32_e32 v84, v84
	v_min_f32_e32 v79, 0, v79
	v_add_f32_e32 v84, 1.0, v84
	v_cmp_gt_f32_e32 vcc, s70, v84
	s_nop 1
	v_cndmask_b32_e64 v85, 0, 32, vcc
	v_ldexp_f32 v84, v84, v85
	v_log_f32_e32 v84, v84
	v_cndmask_b32_e32 v85, 0, v100, vcc
	v_mul_f32_e32 v86, 0x3f317217, v84
	v_fma_f32 v86, v84, s3, -v86
	v_fmac_f32_e32 v86, 0x3377d1cf, v84
	v_fmac_f32_e32 v86, 0x3f317217, v84
	v_cmp_lt_f32_e64 vcc, |v84|, s5
	s_nop 1
	v_cndmask_b32_e32 v84, v84, v86, vcc
	v_sub_f32_e32 v84, v84, v85
	v_sub_f32_e32 v79, v79, v84
	v_fmac_f32_e32 v77, 0x3d800000, v79
	ds_write_b32 v78, v77 offset:520
	ds_read_b128 v[84:87], v76 offset:17280
	ds_read_b128 v[88:91], v76 offset:17296
	ds_read_b128 v[92:95], v76 offset:17312
	ds_read_b128 v[96:99], v76 offset:17328
	s_waitcnt lgkmcnt(3)
	v_fma_f32 v79, v64, v84, v73
	v_fmac_f32_e32 v79, v65, v85
	v_fmac_f32_e32 v79, v62, v86
	v_fmac_f32_e32 v79, v63, v87
	s_waitcnt lgkmcnt(2)
	v_fmac_f32_e32 v79, v60, v88
	v_fmac_f32_e32 v79, v61, v89
	v_fmac_f32_e32 v79, v58, v90
	v_fmac_f32_e32 v79, v59, v91
	s_waitcnt lgkmcnt(1)
	v_fmac_f32_e32 v79, v56, v92
	v_fmac_f32_e32 v79, v57, v93
	v_fmac_f32_e32 v79, v54, v94
	v_fmac_f32_e32 v79, v55, v95
	s_waitcnt lgkmcnt(0)
	v_fmac_f32_e32 v79, v52, v96
	v_fmac_f32_e32 v79, v53, v97
	v_fmac_f32_e32 v79, v42, v98
	v_fmac_f32_e32 v79, v43, v99
	v_mul_f32_e64 v84, |v79|, s2
	v_exp_f32_e32 v84, v84
	v_min_f32_e32 v79, 0, v79
	v_add_f32_e32 v84, 1.0, v84
	v_cmp_gt_f32_e32 vcc, s70, v84
	s_nop 1
	v_cndmask_b32_e64 v85, 0, 32, vcc
	v_ldexp_f32 v84, v84, v85
	v_log_f32_e32 v84, v84
	v_cndmask_b32_e32 v85, 0, v100, vcc
	v_mul_f32_e32 v86, 0x3f317217, v84
	v_fma_f32 v86, v84, s3, -v86
	v_fmac_f32_e32 v86, 0x3377d1cf, v84
	v_fmac_f32_e32 v86, 0x3f317217, v84
	v_cmp_lt_f32_e64 vcc, |v84|, s5
	s_nop 1
	v_cndmask_b32_e32 v84, v84, v86, vcc
	v_sub_f32_e32 v84, v84, v85
	v_sub_f32_e32 v79, v79, v84
	v_fmac_f32_e32 v77, 0x3d800000, v79
	ds_write_b32 v78, v77 offset:780
	ds_read_b128 v[84:87], v76 offset:17344
	ds_read_b128 v[88:91], v76 offset:17360
	ds_read_b128 v[92:95], v76 offset:17376
	ds_read_b128 v[96:99], v76 offset:17392
	s_waitcnt lgkmcnt(3)
	v_fma_f32 v79, v64, v84, v73
	v_fmac_f32_e32 v79, v65, v85
	v_fmac_f32_e32 v79, v62, v86
	v_fmac_f32_e32 v79, v63, v87
	s_waitcnt lgkmcnt(2)
	v_fmac_f32_e32 v79, v60, v88
	v_fmac_f32_e32 v79, v61, v89
	v_fmac_f32_e32 v79, v58, v90
	v_fmac_f32_e32 v79, v59, v91
	s_waitcnt lgkmcnt(1)
	v_fmac_f32_e32 v79, v56, v92
	v_fmac_f32_e32 v79, v57, v93
	v_fmac_f32_e32 v79, v54, v94
	v_fmac_f32_e32 v79, v55, v95
	s_waitcnt lgkmcnt(0)
	v_fmac_f32_e32 v79, v52, v96
	v_fmac_f32_e32 v79, v53, v97
	v_fmac_f32_e32 v79, v42, v98
	v_fmac_f32_e32 v79, v43, v99
	v_mul_f32_e64 v84, |v79|, s2
	v_exp_f32_e32 v84, v84
	v_min_f32_e32 v79, 0, v79
	v_add_f32_e32 v84, 1.0, v84
	v_cmp_gt_f32_e32 vcc, s70, v84
	s_nop 1
	v_cndmask_b32_e64 v85, 0, 32, vcc
	v_ldexp_f32 v84, v84, v85
	v_log_f32_e32 v84, v84
	v_cndmask_b32_e32 v85, 0, v100, vcc
	v_mul_f32_e32 v86, 0x3f317217, v84
	v_fma_f32 v86, v84, s3, -v86
	v_fmac_f32_e32 v86, 0x3377d1cf, v84
	v_fmac_f32_e32 v86, 0x3f317217, v84
	v_cmp_lt_f32_e64 vcc, |v84|, s5
	s_nop 1
	v_cndmask_b32_e32 v84, v84, v86, vcc
	v_sub_f32_e32 v84, v84, v85
	v_sub_f32_e32 v79, v79, v84
	v_fmac_f32_e32 v77, 0x3d800000, v79
	ds_write_b32 v78, v77 offset:1040
	ds_read_b128 v[84:87], v76 offset:17408
	ds_read_b128 v[88:91], v76 offset:17424
	ds_read_b128 v[92:95], v76 offset:17440
	ds_read_b128 v[96:99], v76 offset:17456
	s_waitcnt lgkmcnt(3)
	v_fma_f32 v79, v64, v84, v73
	v_fmac_f32_e32 v79, v65, v85
	v_fmac_f32_e32 v79, v62, v86
	v_fmac_f32_e32 v79, v63, v87
	s_waitcnt lgkmcnt(2)
	v_fmac_f32_e32 v79, v60, v88
	v_fmac_f32_e32 v79, v61, v89
	v_fmac_f32_e32 v79, v58, v90
	v_fmac_f32_e32 v79, v59, v91
	s_waitcnt lgkmcnt(1)
	v_fmac_f32_e32 v79, v56, v92
	v_fmac_f32_e32 v79, v57, v93
	v_fmac_f32_e32 v79, v54, v94
	v_fmac_f32_e32 v79, v55, v95
	s_waitcnt lgkmcnt(0)
	v_fmac_f32_e32 v79, v52, v96
	v_fmac_f32_e32 v79, v53, v97
	v_fmac_f32_e32 v79, v42, v98
	v_fmac_f32_e32 v79, v43, v99
	v_mul_f32_e64 v84, |v79|, s2
	v_exp_f32_e32 v84, v84
	v_min_f32_e32 v79, 0, v79
	v_add_f32_e32 v84, 1.0, v84
	v_cmp_gt_f32_e32 vcc, s70, v84
	s_nop 1
	v_cndmask_b32_e64 v85, 0, 32, vcc
	v_ldexp_f32 v84, v84, v85
	v_log_f32_e32 v84, v84
	v_cndmask_b32_e32 v85, 0, v100, vcc
	v_mul_f32_e32 v86, 0x3f317217, v84
	v_fma_f32 v86, v84, s3, -v86
	v_fmac_f32_e32 v86, 0x3377d1cf, v84
	v_fmac_f32_e32 v86, 0x3f317217, v84
	v_cmp_lt_f32_e64 vcc, |v84|, s5
	s_nop 1
	v_cndmask_b32_e32 v84, v84, v86, vcc
	v_sub_f32_e32 v84, v84, v85
	v_sub_f32_e32 v79, v79, v84
	v_fmac_f32_e32 v77, 0x3d800000, v79
	ds_write_b32 v78, v77 offset:1300
	ds_read_b128 v[84:87], v76 offset:17472
	ds_read_b128 v[88:91], v76 offset:17488
	ds_read_b128 v[92:95], v76 offset:17504
	ds_read_b128 v[96:99], v76 offset:17520
	s_waitcnt lgkmcnt(3)
	v_fma_f32 v79, v64, v84, v73
	v_fmac_f32_e32 v79, v65, v85
	v_fmac_f32_e32 v79, v62, v86
	v_fmac_f32_e32 v79, v63, v87
	s_waitcnt lgkmcnt(2)
	v_fmac_f32_e32 v79, v60, v88
	v_fmac_f32_e32 v79, v61, v89
	v_fmac_f32_e32 v79, v58, v90
	v_fmac_f32_e32 v79, v59, v91
	s_waitcnt lgkmcnt(1)
	v_fmac_f32_e32 v79, v56, v92
	v_fmac_f32_e32 v79, v57, v93
	v_fmac_f32_e32 v79, v54, v94
	v_fmac_f32_e32 v79, v55, v95
	s_waitcnt lgkmcnt(0)
	v_fmac_f32_e32 v79, v52, v96
	v_fmac_f32_e32 v79, v53, v97
	v_fmac_f32_e32 v79, v42, v98
	v_fmac_f32_e32 v79, v43, v99
	v_mul_f32_e64 v84, |v79|, s2
	v_exp_f32_e32 v84, v84
	v_min_f32_e32 v79, 0, v79
	v_add_f32_e32 v84, 1.0, v84
	v_cmp_gt_f32_e32 vcc, s70, v84
	s_nop 1
	v_cndmask_b32_e64 v85, 0, 32, vcc
	v_ldexp_f32 v84, v84, v85
	v_log_f32_e32 v84, v84
	v_cndmask_b32_e32 v85, 0, v100, vcc
	v_mul_f32_e32 v86, 0x3f317217, v84
	v_fma_f32 v86, v84, s3, -v86
	v_fmac_f32_e32 v86, 0x3377d1cf, v84
	v_fmac_f32_e32 v86, 0x3f317217, v84
	v_cmp_lt_f32_e64 vcc, |v84|, s5
	s_nop 1
	v_cndmask_b32_e32 v84, v84, v86, vcc
	v_sub_f32_e32 v84, v84, v85
	v_sub_f32_e32 v79, v79, v84
	v_fmac_f32_e32 v77, 0x3d800000, v79
	ds_write_b32 v78, v77 offset:1560
	ds_read_b128 v[84:87], v76 offset:17536
	ds_read_b128 v[88:91], v76 offset:17552
	ds_read_b128 v[92:95], v76 offset:17568
	ds_read_b128 v[96:99], v76 offset:17584
	s_waitcnt lgkmcnt(3)
	v_fma_f32 v79, v64, v84, v73
	v_fmac_f32_e32 v79, v65, v85
	v_fmac_f32_e32 v79, v62, v86
	v_fmac_f32_e32 v79, v63, v87
	s_waitcnt lgkmcnt(2)
	v_fmac_f32_e32 v79, v60, v88
	v_fmac_f32_e32 v79, v61, v89
	v_fmac_f32_e32 v79, v58, v90
	v_fmac_f32_e32 v79, v59, v91
	s_waitcnt lgkmcnt(1)
	v_fmac_f32_e32 v79, v56, v92
	v_fmac_f32_e32 v79, v57, v93
	v_fmac_f32_e32 v79, v54, v94
	v_fmac_f32_e32 v79, v55, v95
	s_waitcnt lgkmcnt(0)
	v_fmac_f32_e32 v79, v52, v96
	v_fmac_f32_e32 v79, v53, v97
	v_fmac_f32_e32 v79, v42, v98
	v_fmac_f32_e32 v79, v43, v99
	v_mul_f32_e64 v84, |v79|, s2
	v_exp_f32_e32 v84, v84
	v_min_f32_e32 v79, 0, v79
	v_add_f32_e32 v84, 1.0, v84
	v_cmp_gt_f32_e32 vcc, s70, v84
	s_nop 1
	v_cndmask_b32_e64 v85, 0, 32, vcc
	v_ldexp_f32 v84, v84, v85
	v_log_f32_e32 v84, v84
	v_cndmask_b32_e32 v85, 0, v100, vcc
	v_mul_f32_e32 v86, 0x3f317217, v84
	v_fma_f32 v86, v84, s3, -v86
	v_fmac_f32_e32 v86, 0x3377d1cf, v84
	v_fmac_f32_e32 v86, 0x3f317217, v84
	v_cmp_lt_f32_e64 vcc, |v84|, s5
	s_nop 1
	v_cndmask_b32_e32 v84, v84, v86, vcc
	v_sub_f32_e32 v84, v84, v85
	v_sub_f32_e32 v79, v79, v84
	v_fmac_f32_e32 v77, 0x3d800000, v79
	ds_write_b32 v78, v77 offset:1820
	ds_read_b128 v[84:87], v76 offset:17600
	ds_read_b128 v[88:91], v76 offset:17616
	ds_read_b128 v[92:95], v76 offset:17632
	ds_read_b128 v[96:99], v76 offset:17648
	s_waitcnt lgkmcnt(3)
	v_fmac_f32_e32 v73, v64, v84
	v_fmac_f32_e32 v73, v65, v85
	v_fmac_f32_e32 v73, v62, v86
	v_fmac_f32_e32 v73, v63, v87
	s_waitcnt lgkmcnt(2)
	v_fmac_f32_e32 v73, v60, v88
	v_fmac_f32_e32 v73, v61, v89
	v_fmac_f32_e32 v73, v58, v90
	v_fmac_f32_e32 v73, v59, v91
	s_waitcnt lgkmcnt(1)
	v_fmac_f32_e32 v73, v56, v92
	v_fmac_f32_e32 v73, v57, v93
	v_fmac_f32_e32 v73, v54, v94
	v_fmac_f32_e32 v73, v55, v95
	s_waitcnt lgkmcnt(0)
	v_fmac_f32_e32 v73, v52, v96
	v_fmac_f32_e32 v73, v53, v97
	v_fmac_f32_e32 v73, v42, v98
	v_fmac_f32_e32 v73, v43, v99
	v_mul_f32_e64 v42, |v73|, s2
	v_exp_f32_e32 v42, v42
	v_min_f32_e32 v52, 0, v73
	v_add_f32_e32 v42, 1.0, v42
	v_cmp_gt_f32_e32 vcc, s70, v42
	s_nop 1
	v_cndmask_b32_e64 v43, 0, 32, vcc
	v_ldexp_f32 v42, v42, v43
	v_log_f32_e32 v42, v42
	v_cndmask_b32_e32 v53, 0, v100, vcc
	v_add_u32_e32 v43, 0x1e100, v72
	v_mul_f32_e32 v54, 0x3f317217, v42
	v_fma_f32 v54, v42, s3, -v54
	v_fmac_f32_e32 v54, 0x3377d1cf, v42
	v_fmac_f32_e32 v54, 0x3f317217, v42
	v_cmp_lt_f32_e64 vcc, |v42|, s5
	s_nop 1
	v_cndmask_b32_e32 v42, v42, v54, vcc
	v_sub_f32_e32 v42, v42, v53
	v_sub_f32_e32 v42, v52, v42
	v_fmac_f32_e32 v77, 0x3d800000, v42
	v_cmp_lt_i32_e32 vcc, 0, v71
	ds_write_b32 v78, v77 offset:2080
	ds_write_b32 v43, v77
	s_waitcnt lgkmcnt(0)
	s_barrier
	s_and_saveexec_b64 s[2:3], vcc
	s_cbranch_execz .LBB0_81
	s_add_i32 s5, 0, 0x1e100
	v_lshl_add_u32 v43, v40, 2, s5
	v_mov_b32_e32 v42, 0
	s_mov_b64 s[6:7], 0
	v_mov_b32_e32 v52, v71

.LBB0_307:
	s_or_b64 exec, exec, s[2:3]
	v_lshl_or_b32 v1, v47, 5, v48
	v_lshl_add_u32 v0, v49, 1, 0
	s_movk_i32 s6, 0x90
	v_mov_b32_e32 v10, v41
	v_mov_b32_e32 v11, v41
	v_mov_b32_e32 v12, v41
	v_mov_b32_e32 v13, v41
	v_mov_b32_e32 v14, v41
	v_mov_b32_e32 v15, v41
	v_mov_b32_e32 v16, v41
	v_mov_b32_e32 v17, v41
	v_mov_b32_e32 v18, v41
	v_mov_b32_e32 v19, v41
	v_mov_b32_e32 v20, v41
	v_mov_b32_e32 v21, v41
	v_mov_b32_e32 v22, v41
	v_mov_b32_e32 v23, v41
	v_mov_b32_e32 v24, v41
	v_mov_b32_e32 v25, v41
	v_mov_b32_e32 v26, v41
	v_mov_b32_e32 v27, v41
	v_mov_b32_e32 v28, v41
	v_mov_b32_e32 v29, v41
	v_mov_b32_e32 v30, v41
	v_mov_b32_e32 v31, v41
	v_mov_b32_e32 v32, v41
	v_mov_b32_e32 v33, v41
	v_mov_b32_e32 v34, v41
	v_mov_b32_e32 v35, v41
	v_mov_b32_e32 v36, v41
	v_mov_b32_e32 v37, v41
	v_mov_b32_e32 v38, v41
	v_mov_b32_e32 v39, v41
	v_mov_b32_e32 v40, v41
	v_mov_b32_e32 v42, v41
	v_mad_u64_u32 v[8:9], s[2:3], v1, s6, v[0:1]
	s_waitcnt lgkmcnt(0)
	s_barrier
	v_mad_u32_u24 v9, v48, s6, v0
	ds_read_b128 v[0:3], v8 offset:52480
	ds_read_b128 v[4:7], v9 offset:34048
	v_accvgpr_write_b32 a16, v10
	v_accvgpr_write_b32 a17, v11
	v_accvgpr_write_b32 a18, v12
	v_accvgpr_write_b32 a19, v13
	v_accvgpr_write_b32 a20, v14
	v_accvgpr_write_b32 a21, v15
	v_accvgpr_write_b32 a22, v16
	v_accvgpr_write_b32 a23, v17
	v_accvgpr_write_b32 a24, v18
	v_accvgpr_write_b32 a25, v19
	v_accvgpr_write_b32 a26, v20
	v_accvgpr_write_b32 a27, v21
	v_accvgpr_write_b32 a28, v22
	v_accvgpr_write_b32 a29, v23
	v_accvgpr_write_b32 a30, v24
	v_accvgpr_write_b32 a31, v25
	v_accvgpr_write_b32 a0, v26
	v_accvgpr_write_b32 a1, v27
	s_waitcnt lgkmcnt(0)
	v_mfma_f32_32x32x16_f16 a[16:31], v[0:3], v[4:7], a[16:31]
	ds_read_b128 v[4:7], v9 offset:38656
	v_accvgpr_write_b32 a2, v28
	v_accvgpr_write_b32 a3, v29
	v_accvgpr_write_b32 a4, v30
	v_accvgpr_write_b32 a5, v31
	v_accvgpr_write_b32 a6, v32
	v_accvgpr_write_b32 a7, v33
	v_accvgpr_write_b32 a8, v34
	v_accvgpr_write_b32 a9, v35
	v_accvgpr_write_b32 a10, v36
	v_accvgpr_write_b32 a11, v37
	v_accvgpr_write_b32 a12, v38
	v_accvgpr_write_b32 a13, v39
	v_accvgpr_write_b32 a14, v40
	v_accvgpr_write_b32 a15, v42
	s_lshl_b64 s[2:3], s[4:5], 14
	v_readlane_b32 s6, v253, 47
	s_waitcnt lgkmcnt(0)
	v_mfma_f32_32x32x16_f16 a[0:15], v[0:3], v[4:7], a[0:15]
	ds_read_b128 v[0:3], v8 offset:52512
	ds_read_b128 v[4:7], v9 offset:34080
	v_readlane_b32 s7, v253, 48
	s_add_u32 s2, s6, s2
	s_addc_u32 s3, s7, s3
	v_lshlrev_b32_e32 v40, 1, v48
	v_readlane_b32 s12, v253, 2
	v_readlane_b32 s14, v253, 4
	s_waitcnt lgkmcnt(0)
	v_mfma_f32_32x32x16_f16 a[16:31], v[0:3], v[4:7], a[16:31]
	ds_read_b128 v[4:7], v9 offset:38688
	s_bfe_u32 s13, s4, 0x10008
	s_lshl_b32 s13, s13, 2
	s_xor_b32 s4, s4, s13
	s_add_i32 s4, s4, s14
	s_cmpk_lt_i32 s4, 0x800
	v_readlane_b32 s13, v253, 3
	v_readlane_b32 s15, v253, 5
	s_waitcnt lgkmcnt(0)
	v_mfma_f32_32x32x16_f16 a[0:15], v[0:3], v[4:7], a[0:15]
	ds_read_b128 v[0:3], v8 offset:52544
	ds_read_b128 v[4:7], v9 offset:34112
	s_waitcnt lgkmcnt(0)
	v_mfma_f32_32x32x16_f16 a[16:31], v[0:3], v[4:7], a[16:31]
	ds_read_b128 v[4:7], v9 offset:38720
	s_waitcnt lgkmcnt(0)
	v_mfma_f32_32x32x16_f16 a[0:15], v[0:3], v[4:7], a[0:15]
	ds_read_b128 v[0:3], v8 offset:52576
	ds_read_b128 v[4:7], v9 offset:34144
	s_waitcnt lgkmcnt(0)
	v_mfma_f32_32x32x16_f16 a[16:31], v[0:3], v[4:7], a[16:31]
	ds_read_b128 v[4:7], v9 offset:38752
	s_waitcnt lgkmcnt(0)
	v_mfma_f32_32x32x16_f16 a[0:15], v[0:3], v[4:7], a[0:15]
	v_lshl_add_u64 v[0:1], s[2:3], 0, v[40:41]
	s_nop 7
	v_accvgpr_read_b32 v2, a16
	v_cvt_f16_f32_e32 v4, v2
	v_lshlrev_b32_e32 v2, 3, v46
	v_and_b32_e32 v2, 0x100, v2
	v_lshl_or_b32 v2, v47, 11, v2
	v_ashrrev_i32_e32 v3, 31, v2
	v_lshl_add_u64 v[0:1], v[2:3], 1, v[0:1]
	v_accvgpr_read_b32 v2, a17
	v_cvt_f16_f32_e32 v2, v2
	v_accvgpr_read_b32 v3, a18
	v_cvt_f16_f32_e32 v3, v3
	global_store_short v[0:1], v4, off
	global_store_short v[0:1], v2, off offset:128
	v_accvgpr_read_b32 v2, a19
	v_cvt_f16_f32_e32 v2, v2
	global_store_short v[0:1], v3, off offset:256
	v_accvgpr_read_b32 v3, a20
	v_cvt_f16_f32_e32 v3, v3
	global_store_short v[0:1], v2, off offset:384
	v_accvgpr_read_b32 v2, a21
	v_cvt_f16_f32_e32 v2, v2
	global_store_short v[0:1], v3, off offset:1024
	v_accvgpr_read_b32 v3, a22
	v_cvt_f16_f32_e32 v3, v3
	global_store_short v[0:1], v2, off offset:1152
	v_accvgpr_read_b32 v2, a23
	v_cvt_f16_f32_e32 v2, v2
	global_store_short v[0:1], v3, off offset:1280
	v_accvgpr_read_b32 v3, a24
	v_cvt_f16_f32_e32 v3, v3
	global_store_short v[0:1], v2, off offset:1408
	v_accvgpr_read_b32 v2, a25
	v_cvt_f16_f32_e32 v2, v2
	global_store_short v[0:1], v3, off offset:2048
	v_accvgpr_read_b32 v3, a26
	v_cvt_f16_f32_e32 v3, v3
	global_store_short v[0:1], v2, off offset:2176
	v_accvgpr_read_b32 v2, a27
	v_cvt_f16_f32_e32 v2, v2
	global_store_short v[0:1], v3, off offset:2304
	v_accvgpr_read_b32 v3, a28
	v_cvt_f16_f32_e32 v3, v3
	global_store_short v[0:1], v2, off offset:2432
	v_accvgpr_read_b32 v2, a29
	v_cvt_f16_f32_e32 v2, v2
	global_store_short v[0:1], v3, off offset:3072
	v_accvgpr_read_b32 v3, a30
	v_cvt_f16_f32_e32 v3, v3
	global_store_short v[0:1], v2, off offset:3200
	v_accvgpr_read_b32 v2, a31
	v_cvt_f16_f32_e32 v2, v2
	global_store_short v[0:1], v3, off offset:3328
	v_accvgpr_read_b32 v3, a0
	v_cvt_f16_f32_e32 v3, v3
	global_store_short v[0:1], v2, off offset:3456
	v_accvgpr_read_b32 v2, a1
	v_cvt_f16_f32_e32 v2, v2
	global_store_short v[0:1], v3, off offset:64
	v_accvgpr_read_b32 v3, a2
	v_cvt_f16_f32_e32 v3, v3
	global_store_short v[0:1], v2, off offset:192
	v_accvgpr_read_b32 v2, a3
	v_cvt_f16_f32_e32 v2, v2
	global_store_short v[0:1], v3, off offset:320
	v_accvgpr_read_b32 v3, a4
	v_cvt_f16_f32_e32 v3, v3
	global_store_short v[0:1], v2, off offset:448
	v_accvgpr_read_b32 v2, a5
	v_cvt_f16_f32_e32 v2, v2
	global_store_short v[0:1], v3, off offset:1088
	v_accvgpr_read_b32 v3, a6
	v_cvt_f16_f32_e32 v3, v3
	global_store_short v[0:1], v2, off offset:1216
	v_accvgpr_read_b32 v2, a7
	v_cvt_f16_f32_e32 v2, v2
	global_store_short v[0:1], v3, off offset:1344
	v_accvgpr_read_b32 v3, a8
	v_cvt_f16_f32_e32 v3, v3
	global_store_short v[0:1], v2, off offset:1472
	v_accvgpr_read_b32 v2, a9
	v_cvt_f16_f32_e32 v2, v2
	global_store_short v[0:1], v3, off offset:2112
	v_accvgpr_read_b32 v3, a10
	v_cvt_f16_f32_e32 v3, v3
	global_store_short v[0:1], v2, off offset:2240
	v_accvgpr_read_b32 v2, a11
	v_cvt_f16_f32_e32 v2, v2
	global_store_short v[0:1], v3, off offset:2368
	v_accvgpr_read_b32 v3, a12
	v_cvt_f16_f32_e32 v3, v3
	global_store_short v[0:1], v2, off offset:2496
	v_accvgpr_read_b32 v2, a13
	v_cvt_f16_f32_e32 v2, v2
	global_store_short v[0:1], v3, off offset:3136
	v_accvgpr_read_b32 v3, a14
	v_cvt_f16_f32_e32 v3, v3
	global_store_short v[0:1], v2, off offset:3264
	v_accvgpr_read_b32 v2, a15
	v_cvt_f16_f32_e32 v2, v2
	global_store_short v[0:1], v3, off offset:3392
	global_store_short v[0:1], v2, off offset:3520
	s_cbranch_scc0 .LBB0_318
.LBB0_308:
	s_bfe_u32 s5, s4, 0x10008
	s_lshl_b32 s5, s5, 2
	s_xor_b32 s4, s4, s5
	s_and_b32 s5, s4, 7
	s_ashr_i32 s2, s4, 3
	s_lshl_b32 s12, s5, 6
	s_lshl_b32 s3, s2, 6
	s_or_b32 s6, s12, 0x100
	s_add_i32 s7, s12, 0xc40
	s_lshl_b32 s13, s5, 7
	s_cmp_lt_u32 s5, 4
	s_cselect_b32 s6, s6, s7
	s_movk_i32 s7, 0xc40
	s_cselect_b32 s7, 0x200, s7
	v_mbcnt_lo_u32_b32 v46, -1, 0
	v_mbcnt_hi_u32_b32 v46, -1, v46
	s_add_i32 s7, s7, s13
	v_mbcnt_lo_u32_b32 v0, -1, 0
	v_mbcnt_hi_u32_b32 v0, -1, v0
	s_lshl_b32 s90, s7, 1
	v_or_b32_e32 v1, s55, v0
	v_bfe_u32 v2, v0, 5, 1
	v_ashrrev_i32_e32 v1, 5, v1
	s_mov_b32 s7, 0x1ffffffe
	v_lshlrev_b32_e32 v0, 1, v0
	v_readlane_b32 s16, v253, 22
	v_and_or_b32 v4, v1, s7, v2
	v_and_or_b32 v2, v0, 62, s3
	s_waitcnt vmcnt(0)
	v_mov_b64_e32 v[16:17], s[56:57]
	v_or_b32_e32 v24, s16, v46
	v_mad_i64_i32 v[0:1], s[14:15], v2, s68, v[16:17]
	v_or_b32_e32 v2, 1, v2
	v_lshlrev_b32_e32 v4, 3, v4
	v_and_b32_e32 v48, 31, v46
	v_lshrrev_b32_e32 v20, 2, v46
	v_ashrrev_i32_e32 v47, 6, v24
	v_mad_i64_i32 v[2:3], s[14:15], v2, s68, v[16:17]
	v_ashrrev_i32_e32 v5, 31, v4
	v_lshl_or_b32 v22, v48, 1, s3
	v_and_b32_e32 v49, 8, v20
	v_lshl_add_u64 v[0:1], v[0:1], 0, s[90:91]
	v_lshl_add_u64 v[2:3], v[2:3], 0, s[90:91]
	v_lshlrev_b64 v[4:5], 1, v[4:5]
	v_mad_i64_i32 v[18:19], s[14:15], v22, s68, v[16:17]
	v_lshl_or_b32 v26, v47, 4, v49
	v_or_b32_e32 v22, 1, v22
	s_lshl_b32 s6, s6, 1
	v_lshl_add_u64 v[0:1], v[0:1], 0, v[4:5]
	v_lshl_add_u64 v[4:5], v[2:3], 0, v[4:5]
	s_mov_b32 s7, s91
	v_ashrrev_i32_e32 v27, 31, v26
	v_mad_i64_i32 v[16:17], s[14:15], v22, s68, v[16:17]
	global_load_dwordx4 v[8:11], v[0:1], off
	s_nop 0
	global_load_dwordx4 v[0:3], v[0:1], off offset:128
	s_nop 0
	global_load_dwordx4 v[12:15], v[4:5], off
	s_nop 0
	global_load_dwordx4 v[4:7], v[4:5], off offset:128
	v_lshl_add_u64 v[18:19], v[18:19], 0, s[6:7]
	v_lshlrev_b64 v[20:21], 1, v[26:27]
	v_lshl_add_u64 v[16:17], v[16:17], 0, s[6:7]
	v_lshl_add_u64 v[18:19], v[18:19], 0, v[20:21]
	v_lshl_add_u64 v[16:17], v[16:17], 0, v[20:21]
	global_load_dwordx4 v[20:23], v[18:19], off
	s_nop 0
	global_load_dwordx4 v[16:19], v[16:17], off
	s_waitcnt lgkmcnt(0)
	s_barrier
	v_mbcnt_lo_u32_b32 v25, -1, 0
	v_mbcnt_hi_u32_b32 v25, -1, v25
	s_cmp_gt_u32 s5, 3
	v_or_b32_e32 v28, s16, v25
	v_and_b32_e32 v40, 63, v25
	v_ashrrev_i32_e32 v25, 6, v28
	s_mov_b64 s[6:7], -1
	s_cbranch_scc0 .LBB0_314
	s_ashr_i32 s3, s2, 31
	s_lshl_b64 s[2:3], s[2:3], 12
	v_readlane_b32 s6, v254, 17
	s_add_u32 s2, s6, s2
	v_readlane_b32 s6, v254, 18
	s_addc_u32 s3, s6, s3
	s_add_i32 s90, s12, 0xffffff00
	s_lshl_b64 s[6:7], s[90:91], 2
	s_add_u32 s6, s9, s6
	s_addc_u32 s7, s10, s7
	v_lshlrev_b32_e32 v30, 2, v40
	v_mov_b32_e32 v31, v41
	v_lshlrev_b32_e32 v27, 2, v28
	v_lshl_add_u64 v[32:33], s[6:7], 0, v[30:31]
	v_ashrrev_i32_e32 v29, 31, v28
	v_add_u32_e32 v31, 0x400, v27
	v_lshl_add_u64 v[34:35], v[28:29], 2, s[2:3]
	v_and_b32_e32 v36, 0xffffff00, v31
	v_add_u32_e32 v31, 0x800, v27
	v_and_b32_e32 v38, 0xffffff00, v31
	global_load_dword v31, v[34:35], off
	global_load_dword v42, v[34:35], off offset:1024
	global_load_dword v43, v[34:35], off offset:2048
	global_load_dword v44, v[34:35], off offset:3072
	v_add_u32_e32 v34, 0xc00, v27
	v_and_b32_e32 v28, 0xffffff00, v27
	v_and_b32_e32 v34, 0xffffff00, v34
	v_ashrrev_i32_e32 v29, 31, v28
	v_ashrrev_i32_e32 v37, 31, v36
	v_ashrrev_i32_e32 v39, 31, v38
	v_ashrrev_i32_e32 v35, 31, v34
	v_lshl_add_u64 v[28:29], v[28:29], 2, v[32:33]
	v_lshl_add_u64 v[36:37], v[36:37], 2, v[32:33]
	v_lshl_add_u64 v[38:39], v[38:39], 2, v[32:33]
	v_lshl_add_u64 v[32:33], v[34:35], 2, v[32:33]
	global_load_dword v34, v[28:29], off
	global_load_dword v35, v[36:37], off
	s_nop 0
	global_load_dword v36, v[38:39], off
	s_nop 0
	global_load_dword v32, v[32:33], off
	s_add_u32 s2, s12, s8
	s_addc_u32 s3, 0, s11
	v_readlane_b32 s12, v253, 6
	v_lshl_add_u64 v[28:29], v[40:41], 0, s[2:3]
	v_readlane_b32 s14, v253, 8
	v_readlane_b32 s15, v253, 9
	v_add_u32_e32 v27, 0, v27
	v_add_u32_e32 v55, 0, v30
	v_lshl_add_u64 v[28:29], v[28:29], 2, s[14:15]
	v_lshl_add_u32 v53, v25, 10, 0
	s_mov_b32 s2, 0xbfb8aa3b
	s_movk_i32 s3, 0x1040
	v_mul_lo_u32 v54, v25, s3
	s_mov_b32 s3, 0x3f317217
	s_waitcnt vmcnt(22)
	v_mov_b32_e32 v73, 0x41b17218
	s_mov_b32 s6, 0x7f800000
	s_mov_b32 s7, 0x3d800000
	v_lshl_or_b32 v72, v25, 4, 1
	v_readlane_b32 s13, v253, 7
	v_readlane_b32 s16, v253, 10
	v_readlane_b32 s17, v253, 11
	v_readlane_b32 s18, v253, 12
	v_readlane_b32 s19, v253, 13
	v_readlane_b32 s20, v253, 14
	v_readlane_b32 s21, v253, 15
	v_readlane_b32 s22, v253, 16
	v_readlane_b32 s23, v253, 17
	v_readlane_b32 s24, v253, 18
	v_readlane_b32 s25, v253, 19
	v_readlane_b32 s26, v253, 20
	v_readlane_b32 s27, v253, 21
	s_waitcnt vmcnt(6)
	ds_write2st64_b32 v27, v31, v42 offset0:65 offset1:69
	s_waitcnt vmcnt(4)
	ds_write2st64_b32 v27, v43, v44 offset0:73 offset1:77
	s_waitcnt vmcnt(2)
	ds_write2st64_b32 v27, v34, v35 offset0:81 offset1:85
	s_waitcnt vmcnt(0)
	ds_write2st64_b32 v27, v36, v32 offset0:89 offset1:93
	s_waitcnt lgkmcnt(0)
	s_barrier
	global_load_dword v50, v[28:29], off offset:-1024
	ds_read2st64_b32 v[44:45], v55 offset0:81 offset1:82
	ds_read2st64_b32 v[42:43], v55 offset0:83 offset1:84
	ds_read2st64_b32 v[38:39], v55 offset0:85 offset1:86
	ds_read2st64_b32 v[36:37], v55 offset0:87 offset1:88
	ds_read_b128 v[56:59], v53 offset:16640
	ds_read2st64_b32 v[34:35], v55 offset0:89 offset1:90
	ds_read2st64_b32 v[32:33], v55 offset0:91 offset1:92
	ds_read2st64_b32 v[30:31], v55 offset0:93 offset1:94
	ds_read2st64_b32 v[28:29], v55 offset0:95 offset1:96
	ds_read_b128 v[60:63], v53 offset:16656
	ds_read_b128 v[64:67], v53 offset:16672
	ds_read_b128 v[68:71], v53 offset:16688
	v_add_u32_e32 v27, 0x1e100, v27
	s_waitcnt vmcnt(0) lgkmcnt(7)
	v_fma_f32 v52, v44, v56, v50
	v_fmac_f32_e32 v52, v45, v57
	v_fmac_f32_e32 v52, v42, v58
	v_fmac_f32_e32 v52, v43, v59
	s_waitcnt lgkmcnt(2)
	v_fmac_f32_e32 v52, v38, v60
	v_fmac_f32_e32 v52, v39, v61
	v_fmac_f32_e32 v52, v36, v62
	v_fmac_f32_e32 v52, v37, v63
	s_waitcnt lgkmcnt(1)
	v_fmac_f32_e32 v52, v34, v64
	v_fmac_f32_e32 v52, v35, v65
	v_fmac_f32_e32 v52, v32, v66
	v_fmac_f32_e32 v52, v33, v67
	s_waitcnt lgkmcnt(0)
	v_fmac_f32_e32 v52, v30, v68
	v_fmac_f32_e32 v52, v31, v69
	v_fmac_f32_e32 v52, v28, v70
	v_fmac_f32_e32 v52, v29, v71
	v_mul_f32_e64 v51, |v52|, s2
	v_exp_f32_e32 v51, v51
	v_min_f32_e32 v52, 0, v52
	v_lshl_add_u32 v68, v72, 6, 0
	v_add_f32_e32 v51, 1.0, v51
	v_cmp_gt_f32_e32 vcc, s70, v51
	s_nop 1
	v_cndmask_b32_e64 v56, 0, 32, vcc
	v_ldexp_f32 v51, v51, v56
	v_log_f32_e32 v56, v51
	v_add_u32_e32 v51, v55, v54
	v_cndmask_b32_e32 v54, 0, v73, vcc
	v_mul_f32_e32 v57, 0x3f317217, v56
	v_fma_f32 v57, v56, s3, -v57
	v_fmac_f32_e32 v57, 0x3377d1cf, v56
	v_fmac_f32_e32 v57, 0x3f317217, v56
	v_cmp_lt_f32_e64 vcc, |v56|, s6
	s_nop 1
	v_cndmask_b32_e32 v56, v56, v57, vcc
	v_sub_f32_e32 v54, v56, v54
	v_sub_f32_e32 v52, v52, v54
	v_fma_f32 v54, v52, s7, 0
	ds_write_b32 v51, v54
	ds_read_b128 v[56:59], v68 offset:16640
	ds_read_b128 v[60:63], v68 offset:16656
	ds_read_b128 v[64:67], v68 offset:16672
	ds_read_b128 v[68:71], v68 offset:16688
	s_movk_i32 s7, 0x104
	s_waitcnt lgkmcnt(3)
	v_fma_f32 v56, v44, v56, v50
	v_fmac_f32_e32 v56, v45, v57
	v_fmac_f32_e32 v56, v42, v58
	v_fmac_f32_e32 v56, v43, v59
	s_waitcnt lgkmcnt(2)
	v_fmac_f32_e32 v56, v38, v60
	v_fmac_f32_e32 v56, v39, v61
	v_fmac_f32_e32 v56, v36, v62
	v_fmac_f32_e32 v56, v37, v63
	s_waitcnt lgkmcnt(1)
	v_fmac_f32_e32 v56, v34, v64
	v_fmac_f32_e32 v56, v35, v65
	v_fmac_f32_e32 v56, v32, v66
	v_fmac_f32_e32 v56, v33, v67
	s_waitcnt lgkmcnt(0)
	v_fmac_f32_e32 v56, v30, v68
	v_fmac_f32_e32 v56, v31, v69
	v_fmac_f32_e32 v56, v28, v70
	v_fmac_f32_e32 v56, v29, v71
	v_mul_f32_e64 v52, |v56|, s2
	v_exp_f32_e32 v52, v52
	v_min_f32_e32 v56, 0, v56
	v_mul_lo_u32 v72, v72, s7
	v_add_f32_e32 v52, 1.0, v52
	v_cmp_gt_f32_e32 vcc, s70, v52
	s_nop 1
	v_cndmask_b32_e64 v57, 0, 32, vcc
	v_ldexp_f32 v52, v52, v57
	v_log_f32_e32 v57, v52
	v_cndmask_b32_e32 v58, 0, v73, vcc
	v_add_u32_e32 v52, v55, v72
	v_mul_f32_e32 v59, 0x3f317217, v57
	v_fma_f32 v59, v57, s3, -v59
	v_fmac_f32_e32 v59, 0x3377d1cf, v57
	v_fmac_f32_e32 v59, 0x3f317217, v57
	v_cmp_lt_f32_e64 vcc, |v57|, s6
	s_nop 1
	v_cndmask_b32_e32 v57, v57, v59, vcc
	v_sub_f32_e32 v57, v57, v58
	v_sub_f32_e32 v56, v56, v57
	v_fmac_f32_e32 v54, 0x3d800000, v56
	ds_write_b32 v52, v54
	ds_read_b128 v[56:59], v53 offset:16768
	ds_read_b128 v[60:63], v53 offset:16784
	ds_read_b128 v[64:67], v53 offset:16800
	ds_read_b128 v[68:71], v53 offset:16816
	s_waitcnt lgkmcnt(3)
	v_fma_f32 v56, v44, v56, v50
	v_fmac_f32_e32 v56, v45, v57
	v_fmac_f32_e32 v56, v42, v58
	v_fmac_f32_e32 v56, v43, v59
	s_waitcnt lgkmcnt(2)
	v_fmac_f32_e32 v56, v38, v60
	v_fmac_f32_e32 v56, v39, v61
	v_fmac_f32_e32 v56, v36, v62
	v_fmac_f32_e32 v56, v37, v63
	s_waitcnt lgkmcnt(1)
	v_fmac_f32_e32 v56, v34, v64
	v_fmac_f32_e32 v56, v35, v65
	v_fmac_f32_e32 v56, v32, v66
	v_fmac_f32_e32 v56, v33, v67
	s_waitcnt lgkmcnt(0)
	v_fmac_f32_e32 v56, v30, v68
	v_fmac_f32_e32 v56, v31, v69
	v_fmac_f32_e32 v56, v28, v70
	v_fmac_f32_e32 v56, v29, v71
	v_mul_f32_e64 v57, |v56|, s2
	v_exp_f32_e32 v57, v57
	v_min_f32_e32 v56, 0, v56
	v_add_f32_e32 v57, 1.0, v57
	v_cmp_gt_f32_e32 vcc, s70, v57
	s_nop 1
	v_cndmask_b32_e64 v58, 0, 32, vcc
	v_ldexp_f32 v57, v57, v58
	v_log_f32_e32 v57, v57
	v_cndmask_b32_e32 v58, 0, v73, vcc
	v_mul_f32_e32 v59, 0x3f317217, v57
	v_fma_f32 v59, v57, s3, -v59
	v_fmac_f32_e32 v59, 0x3377d1cf, v57
	v_fmac_f32_e32 v59, 0x3f317217, v57
	v_cmp_lt_f32_e64 vcc, |v57|, s6
	s_nop 1
	v_cndmask_b32_e32 v57, v57, v59, vcc
	v_sub_f32_e32 v57, v57, v58
	v_sub_f32_e32 v56, v56, v57
	v_fmac_f32_e32 v54, 0x3d800000, v56
	ds_write_b32 v52, v54 offset:260
	ds_read_b128 v[56:59], v53 offset:16832
	ds_read_b128 v[60:63], v53 offset:16848
	ds_read_b128 v[64:67], v53 offset:16864
	ds_read_b128 v[68:71], v53 offset:16880
	s_waitcnt lgkmcnt(3)
	v_fma_f32 v56, v44, v56, v50
	v_fmac_f32_e32 v56, v45, v57
	v_fmac_f32_e32 v56, v42, v58
	v_fmac_f32_e32 v56, v43, v59
	s_waitcnt lgkmcnt(2)
	v_fmac_f32_e32 v56, v38, v60
	v_fmac_f32_e32 v56, v39, v61
	v_fmac_f32_e32 v56, v36, v62
	v_fmac_f32_e32 v56, v37, v63
	s_waitcnt lgkmcnt(1)
	v_fmac_f32_e32 v56, v34, v64
	v_fmac_f32_e32 v56, v35, v65
	v_fmac_f32_e32 v56, v32, v66
	v_fmac_f32_e32 v56, v33, v67
	s_waitcnt lgkmcnt(0)
	v_fmac_f32_e32 v56, v30, v68
	v_fmac_f32_e32 v56, v31, v69
	v_fmac_f32_e32 v56, v28, v70
	v_fmac_f32_e32 v56, v29, v71
	v_mul_f32_e64 v57, |v56|, s2
	v_exp_f32_e32 v57, v57
	v_min_f32_e32 v56, 0, v56
	v_add_f32_e32 v57, 1.0, v57
	v_cmp_gt_f32_e32 vcc, s70, v57
	s_nop 1
	v_cndmask_b32_e64 v58, 0, 32, vcc
	v_ldexp_f32 v57, v57, v58
	v_log_f32_e32 v57, v57
	v_cndmask_b32_e32 v58, 0, v73, vcc
	v_mul_f32_e32 v59, 0x3f317217, v57
	v_fma_f32 v59, v57, s3, -v59
	v_fmac_f32_e32 v59, 0x3377d1cf, v57
	v_fmac_f32_e32 v59, 0x3f317217, v57
	v_cmp_lt_f32_e64 vcc, |v57|, s6
	s_nop 1
	v_cndmask_b32_e32 v57, v57, v59, vcc
	v_sub_f32_e32 v57, v57, v58
	v_sub_f32_e32 v56, v56, v57
	v_fmac_f32_e32 v54, 0x3d800000, v56
	ds_write_b32 v52, v54 offset:520
	ds_read_b128 v[56:59], v53 offset:16896
	ds_read_b128 v[60:63], v53 offset:16912
	ds_read_b128 v[64:67], v53 offset:16928
	ds_read_b128 v[68:71], v53 offset:16944
	s_waitcnt lgkmcnt(3)
	v_fma_f32 v56, v44, v56, v50
	v_fmac_f32_e32 v56, v45, v57
	v_fmac_f32_e32 v56, v42, v58
	v_fmac_f32_e32 v56, v43, v59
	s_waitcnt lgkmcnt(2)
	v_fmac_f32_e32 v56, v38, v60
	v_fmac_f32_e32 v56, v39, v61
	v_fmac_f32_e32 v56, v36, v62
	v_fmac_f32_e32 v56, v37, v63
	s_waitcnt lgkmcnt(1)
	v_fmac_f32_e32 v56, v34, v64
	v_fmac_f32_e32 v56, v35, v65
	v_fmac_f32_e32 v56, v32, v66
	v_fmac_f32_e32 v56, v33, v67
	s_waitcnt lgkmcnt(0)
	v_fmac_f32_e32 v56, v30, v68
	v_fmac_f32_e32 v56, v31, v69
	v_fmac_f32_e32 v56, v28, v70
	v_fmac_f32_e32 v56, v29, v71
	v_mul_f32_e64 v57, |v56|, s2
	v_exp_f32_e32 v57, v57
	v_min_f32_e32 v56, 0, v56
	v_add_f32_e32 v57, 1.0, v57
	v_cmp_gt_f32_e32 vcc, s70, v57
	s_nop 1
	v_cndmask_b32_e64 v58, 0, 32, vcc
	v_ldexp_f32 v57, v57, v58
	v_log_f32_e32 v57, v57
	v_cndmask_b32_e32 v58, 0, v73, vcc
	v_mul_f32_e32 v59, 0x3f317217, v57
	v_fma_f32 v59, v57, s3, -v59
	v_fmac_f32_e32 v59, 0x3377d1cf, v57
	v_fmac_f32_e32 v59, 0x3f317217, v57
	v_cmp_lt_f32_e64 vcc, |v57|, s6
	s_nop 1
	v_cndmask_b32_e32 v57, v57, v59, vcc
	v_sub_f32_e32 v57, v57, v58
	v_sub_f32_e32 v56, v56, v57
	v_fmac_f32_e32 v54, 0x3d800000, v56
	ds_write_b32 v52, v54 offset:780
	ds_read_b128 v[56:59], v53 offset:16960
	ds_read_b128 v[60:63], v53 offset:16976
	ds_read_b128 v[64:67], v53 offset:16992
	ds_read_b128 v[68:71], v53 offset:17008
	s_waitcnt lgkmcnt(3)
	v_fma_f32 v56, v44, v56, v50
	v_fmac_f32_e32 v56, v45, v57
	v_fmac_f32_e32 v56, v42, v58
	v_fmac_f32_e32 v56, v43, v59
	s_waitcnt lgkmcnt(2)
	v_fmac_f32_e32 v56, v38, v60
	v_fmac_f32_e32 v56, v39, v61
	v_fmac_f32_e32 v56, v36, v62
	v_fmac_f32_e32 v56, v37, v63
	s_waitcnt lgkmcnt(1)
	v_fmac_f32_e32 v56, v34, v64
	v_fmac_f32_e32 v56, v35, v65
	v_fmac_f32_e32 v56, v32, v66
	v_fmac_f32_e32 v56, v33, v67
	s_waitcnt lgkmcnt(0)
	v_fmac_f32_e32 v56, v30, v68
	v_fmac_f32_e32 v56, v31, v69
	v_fmac_f32_e32 v56, v28, v70
	v_fmac_f32_e32 v56, v29, v71
	v_mul_f32_e64 v57, |v56|, s2
	v_exp_f32_e32 v57, v57
	v_min_f32_e32 v56, 0, v56
	v_add_f32_e32 v57, 1.0, v57
	v_cmp_gt_f32_e32 vcc, s70, v57
	s_nop 1
	v_cndmask_b32_e64 v58, 0, 32, vcc
	v_ldexp_f32 v57, v57, v58
	v_log_f32_e32 v57, v57
	v_cndmask_b32_e32 v58, 0, v73, vcc
	v_mul_f32_e32 v59, 0x3f317217, v57
	v_fma_f32 v59, v57, s3, -v59
	v_fmac_f32_e32 v59, 0x3377d1cf, v57
	v_fmac_f32_e32 v59, 0x3f317217, v57
	v_cmp_lt_f32_e64 vcc, |v57|, s6
	s_nop 1
	v_cndmask_b32_e32 v57, v57, v59, vcc
	v_sub_f32_e32 v57, v57, v58
	v_sub_f32_e32 v56, v56, v57
	v_fmac_f32_e32 v54, 0x3d800000, v56
	ds_write_b32 v52, v54 offset:1040
	ds_read_b128 v[56:59], v53 offset:17024
	ds_read_b128 v[60:63], v53 offset:17040
	ds_read_b128 v[64:67], v53 offset:17056
	ds_read_b128 v[68:71], v53 offset:17072
	s_waitcnt lgkmcnt(3)
	v_fma_f32 v56, v44, v56, v50
	v_fmac_f32_e32 v56, v45, v57
	v_fmac_f32_e32 v56, v42, v58
	v_fmac_f32_e32 v56, v43, v59
	s_waitcnt lgkmcnt(2)
	v_fmac_f32_e32 v56, v38, v60
	v_fmac_f32_e32 v56, v39, v61
	v_fmac_f32_e32 v56, v36, v62
	v_fmac_f32_e32 v56, v37, v63
	s_waitcnt lgkmcnt(1)
	v_fmac_f32_e32 v56, v34, v64
	v_fmac_f32_e32 v56, v35, v65
	v_fmac_f32_e32 v56, v32, v66
	v_fmac_f32_e32 v56, v33, v67
	s_waitcnt lgkmcnt(0)
	v_fmac_f32_e32 v56, v30, v68
	v_fmac_f32_e32 v56, v31, v69
	v_fmac_f32_e32 v56, v28, v70
	v_fmac_f32_e32 v56, v29, v71
	v_mul_f32_e64 v57, |v56|, s2
	v_exp_f32_e32 v57, v57
	v_min_f32_e32 v56, 0, v56
	v_add_f32_e32 v57, 1.0, v57
	v_cmp_gt_f32_e32 vcc, s70, v57
	s_nop 1
	v_cndmask_b32_e64 v58, 0, 32, vcc
	v_ldexp_f32 v57, v57, v58
	v_log_f32_e32 v57, v57
	v_cndmask_b32_e32 v58, 0, v73, vcc
	v_mul_f32_e32 v59, 0x3f317217, v57
	v_fma_f32 v59, v57, s3, -v59
	v_fmac_f32_e32 v59, 0x3377d1cf, v57
	v_fmac_f32_e32 v59, 0x3f317217, v57
	v_cmp_lt_f32_e64 vcc, |v57|, s6
	s_nop 1
	v_cndmask_b32_e32 v57, v57, v59, vcc
	v_sub_f32_e32 v57, v57, v58
	v_sub_f32_e32 v56, v56, v57
	v_fmac_f32_e32 v54, 0x3d800000, v56
	ds_write_b32 v52, v54 offset:1300
	ds_read_b128 v[56:59], v53 offset:17088
	ds_read_b128 v[60:63], v53 offset:17104
	ds_read_b128 v[64:67], v53 offset:17120
	ds_read_b128 v[68:71], v53 offset:17136
	s_waitcnt lgkmcnt(3)
	v_fma_f32 v56, v44, v56, v50
	v_fmac_f32_e32 v56, v45, v57
	v_fmac_f32_e32 v56, v42, v58
	v_fmac_f32_e32 v56, v43, v59
	s_waitcnt lgkmcnt(2)
	v_fmac_f32_e32 v56, v38, v60
	v_fmac_f32_e32 v56, v39, v61
	v_fmac_f32_e32 v56, v36, v62
	v_fmac_f32_e32 v56, v37, v63
	s_waitcnt lgkmcnt(1)
	v_fmac_f32_e32 v56, v34, v64
	v_fmac_f32_e32 v56, v35, v65
	v_fmac_f32_e32 v56, v32, v66
	v_fmac_f32_e32 v56, v33, v67
	s_waitcnt lgkmcnt(0)
	v_fmac_f32_e32 v56, v30, v68
	v_fmac_f32_e32 v56, v31, v69
	v_fmac_f32_e32 v56, v28, v70
	v_fmac_f32_e32 v56, v29, v71
	v_mul_f32_e64 v57, |v56|, s2
	v_exp_f32_e32 v57, v57
	v_add_u32_e32 v58, 0x618, v72
	v_add_u32_e32 v55, v55, v58
	v_min_f32_e32 v56, 0, v56
	v_add_f32_e32 v57, 1.0, v57
	v_cmp_gt_f32_e32 vcc, s70, v57
	s_nop 1
	v_cndmask_b32_e64 v59, 0, 32, vcc
	v_ldexp_f32 v57, v57, v59
	v_log_f32_e32 v57, v57
	v_cndmask_b32_e32 v58, 0, v73, vcc
	v_mul_f32_e32 v59, 0x3f317217, v57
	v_fma_f32 v59, v57, s3, -v59
	v_fmac_f32_e32 v59, 0x3377d1cf, v57
	v_fmac_f32_e32 v59, 0x3f317217, v57
	v_cmp_lt_f32_e64 vcc, |v57|, s6
	s_nop 1
	v_cndmask_b32_e32 v57, v57, v59, vcc
	v_sub_f32_e32 v57, v57, v58
	v_sub_f32_e32 v56, v56, v57
	v_fmac_f32_e32 v54, 0x3d800000, v56
	ds_write_b32 v55, v54
	ds_read_b128 v[56:59], v53 offset:17152
	ds_read_b128 v[60:63], v53 offset:17168
	ds_read_b128 v[64:67], v53 offset:17184
	ds_read_b128 v[68:71], v53 offset:17200
	s_waitcnt lgkmcnt(3)
	v_fma_f32 v56, v44, v56, v50
	v_fmac_f32_e32 v56, v45, v57
	v_fmac_f32_e32 v56, v42, v58
	v_fmac_f32_e32 v56, v43, v59
	s_waitcnt lgkmcnt(2)
	v_fmac_f32_e32 v56, v38, v60
	v_fmac_f32_e32 v56, v39, v61
	v_fmac_f32_e32 v56, v36, v62
	v_fmac_f32_e32 v56, v37, v63
	s_waitcnt lgkmcnt(1)
	v_fmac_f32_e32 v56, v34, v64
	v_fmac_f32_e32 v56, v35, v65
	v_fmac_f32_e32 v56, v32, v66
	v_fmac_f32_e32 v56, v33, v67
	s_waitcnt lgkmcnt(0)
	v_fmac_f32_e32 v56, v30, v68
	v_fmac_f32_e32 v56, v31, v69
	v_fmac_f32_e32 v56, v28, v70
	v_fmac_f32_e32 v56, v29, v71
	v_mul_f32_e64 v57, |v56|, s2
	v_exp_f32_e32 v57, v57
	v_min_f32_e32 v56, 0, v56
	v_add_f32_e32 v57, 1.0, v57
	v_cmp_gt_f32_e32 vcc, s70, v57
	s_nop 1
	v_cndmask_b32_e64 v58, 0, 32, vcc
	v_ldexp_f32 v57, v57, v58
	v_log_f32_e32 v57, v57
	v_cndmask_b32_e32 v58, 0, v73, vcc
	v_mul_f32_e32 v59, 0x3f317217, v57
	v_fma_f32 v59, v57, s3, -v59
	v_fmac_f32_e32 v59, 0x3377d1cf, v57
	v_fmac_f32_e32 v59, 0x3f317217, v57
	v_cmp_lt_f32_e64 vcc, |v57|, s6
	s_nop 1
	v_cndmask_b32_e32 v57, v57, v59, vcc
	v_sub_f32_e32 v57, v57, v58
	v_sub_f32_e32 v56, v56, v57
	v_fmac_f32_e32 v54, 0x3d800000, v56
	ds_write_b32 v55, v54 offset:260
	ds_read_b128 v[56:59], v53 offset:17216
	ds_read_b128 v[60:63], v53 offset:17232
	ds_read_b128 v[64:67], v53 offset:17248
	ds_read_b128 v[68:71], v53 offset:17264
	s_waitcnt lgkmcnt(3)
	v_fma_f32 v56, v44, v56, v50
	v_fmac_f32_e32 v56, v45, v57
	v_fmac_f32_e32 v56, v42, v58
	v_fmac_f32_e32 v56, v43, v59
	s_waitcnt lgkmcnt(2)
	v_fmac_f32_e32 v56, v38, v60
	v_fmac_f32_e32 v56, v39, v61
	v_fmac_f32_e32 v56, v36, v62
	v_fmac_f32_e32 v56, v37, v63
	s_waitcnt lgkmcnt(1)
	v_fmac_f32_e32 v56, v34, v64
	v_fmac_f32_e32 v56, v35, v65
	v_fmac_f32_e32 v56, v32, v66
	v_fmac_f32_e32 v56, v33, v67
	s_waitcnt lgkmcnt(0)
	v_fmac_f32_e32 v56, v30, v68
	v_fmac_f32_e32 v56, v31, v69
	v_fmac_f32_e32 v56, v28, v70
	v_fmac_f32_e32 v56, v29, v71
	v_mul_f32_e64 v57, |v56|, s2
	v_exp_f32_e32 v57, v57
	v_min_f32_e32 v56, 0, v56
	v_add_f32_e32 v57, 1.0, v57
	v_cmp_gt_f32_e32 vcc, s70, v57
	s_nop 1
	v_cndmask_b32_e64 v58, 0, 32, vcc
	v_ldexp_f32 v57, v57, v58
	v_log_f32_e32 v57, v57
	v_cndmask_b32_e32 v58, 0, v73, vcc
	v_mul_f32_e32 v59, 0x3f317217, v57
	v_fma_f32 v59, v57, s3, -v59
	v_fmac_f32_e32 v59, 0x3377d1cf, v57
	v_fmac_f32_e32 v59, 0x3f317217, v57
	v_cmp_lt_f32_e64 vcc, |v57|, s6
	s_nop 1
	v_cndmask_b32_e32 v57, v57, v59, vcc
	v_sub_f32_e32 v57, v57, v58
	v_sub_f32_e32 v56, v56, v57
	v_fmac_f32_e32 v54, 0x3d800000, v56
	ds_write_b32 v55, v54 offset:520
	ds_read_b128 v[56:59], v53 offset:17280
	ds_read_b128 v[60:63], v53 offset:17296
	ds_read_b128 v[64:67], v53 offset:17312
	ds_read_b128 v[68:71], v53 offset:17328
	s_waitcnt lgkmcnt(3)
	v_fma_f32 v56, v44, v56, v50
	v_fmac_f32_e32 v56, v45, v57
	v_fmac_f32_e32 v56, v42, v58
	v_fmac_f32_e32 v56, v43, v59
	s_waitcnt lgkmcnt(2)
	v_fmac_f32_e32 v56, v38, v60
	v_fmac_f32_e32 v56, v39, v61
	v_fmac_f32_e32 v56, v36, v62
	v_fmac_f32_e32 v56, v37, v63
	s_waitcnt lgkmcnt(1)
	v_fmac_f32_e32 v56, v34, v64
	v_fmac_f32_e32 v56, v35, v65
	v_fmac_f32_e32 v56, v32, v66
	v_fmac_f32_e32 v56, v33, v67
	s_waitcnt lgkmcnt(0)
	v_fmac_f32_e32 v56, v30, v68
	v_fmac_f32_e32 v56, v31, v69
	v_fmac_f32_e32 v56, v28, v70
	v_fmac_f32_e32 v56, v29, v71
	v_mul_f32_e64 v57, |v56|, s2
	v_exp_f32_e32 v57, v57
	v_min_f32_e32 v56, 0, v56
	v_add_f32_e32 v57, 1.0, v57
	v_cmp_gt_f32_e32 vcc, s70, v57
	s_nop 1
	v_cndmask_b32_e64 v58, 0, 32, vcc
	v_ldexp_f32 v57, v57, v58
	v_log_f32_e32 v57, v57
	v_cndmask_b32_e32 v58, 0, v73, vcc
	v_mul_f32_e32 v59, 0x3f317217, v57
	v_fma_f32 v59, v57, s3, -v59
	v_fmac_f32_e32 v59, 0x3377d1cf, v57
	v_fmac_f32_e32 v59, 0x3f317217, v57
	v_cmp_lt_f32_e64 vcc, |v57|, s6
	s_nop 1
	v_cndmask_b32_e32 v57, v57, v59, vcc
	v_sub_f32_e32 v57, v57, v58
	v_sub_f32_e32 v56, v56, v57
	v_fmac_f32_e32 v54, 0x3d800000, v56
	ds_write_b32 v55, v54 offset:780
	ds_read_b128 v[56:59], v53 offset:17344
	ds_read_b128 v[60:63], v53 offset:17360
	ds_read_b128 v[64:67], v53 offset:17376
	ds_read_b128 v[68:71], v53 offset:17392
	s_waitcnt lgkmcnt(3)
	v_fma_f32 v56, v44, v56, v50
	v_fmac_f32_e32 v56, v45, v57
	v_fmac_f32_e32 v56, v42, v58
	v_fmac_f32_e32 v56, v43, v59
	s_waitcnt lgkmcnt(2)
	v_fmac_f32_e32 v56, v38, v60
	v_fmac_f32_e32 v56, v39, v61
	v_fmac_f32_e32 v56, v36, v62
	v_fmac_f32_e32 v56, v37, v63
	s_waitcnt lgkmcnt(1)
	v_fmac_f32_e32 v56, v34, v64
	v_fmac_f32_e32 v56, v35, v65
	v_fmac_f32_e32 v56, v32, v66
	v_fmac_f32_e32 v56, v33, v67
	s_waitcnt lgkmcnt(0)
	v_fmac_f32_e32 v56, v30, v68
	v_fmac_f32_e32 v56, v31, v69
	v_fmac_f32_e32 v56, v28, v70
	v_fmac_f32_e32 v56, v29, v71
	v_mul_f32_e64 v57, |v56|, s2
	v_exp_f32_e32 v57, v57
	v_min_f32_e32 v56, 0, v56
	v_add_f32_e32 v57, 1.0, v57
	v_cmp_gt_f32_e32 vcc, s70, v57
	s_nop 1
	v_cndmask_b32_e64 v58, 0, 32, vcc
	v_ldexp_f32 v57, v57, v58
	v_log_f32_e32 v57, v57
	v_cndmask_b32_e32 v58, 0, v73, vcc
	v_mul_f32_e32 v59, 0x3f317217, v57
	v_fma_f32 v59, v57, s3, -v59
	v_fmac_f32_e32 v59, 0x3377d1cf, v57
	v_fmac_f32_e32 v59, 0x3f317217, v57
	v_cmp_lt_f32_e64 vcc, |v57|, s6
	s_nop 1
	v_cndmask_b32_e32 v57, v57, v59, vcc
	v_sub_f32_e32 v57, v57, v58
	v_sub_f32_e32 v56, v56, v57
	v_fmac_f32_e32 v54, 0x3d800000, v56
	ds_write_b32 v55, v54 offset:1040
	ds_read_b128 v[56:59], v53 offset:17408
	ds_read_b128 v[60:63], v53 offset:17424
	ds_read_b128 v[64:67], v53 offset:17440
	ds_read_b128 v[68:71], v53 offset:17456
	s_waitcnt lgkmcnt(3)
	v_fma_f32 v56, v44, v56, v50
	v_fmac_f32_e32 v56, v45, v57
	v_fmac_f32_e32 v56, v42, v58
	v_fmac_f32_e32 v56, v43, v59
	s_waitcnt lgkmcnt(2)
	v_fmac_f32_e32 v56, v38, v60
	v_fmac_f32_e32 v56, v39, v61
	v_fmac_f32_e32 v56, v36, v62
	v_fmac_f32_e32 v56, v37, v63
	s_waitcnt lgkmcnt(1)
	v_fmac_f32_e32 v56, v34, v64
	v_fmac_f32_e32 v56, v35, v65
	v_fmac_f32_e32 v56, v32, v66
	v_fmac_f32_e32 v56, v33, v67
	s_waitcnt lgkmcnt(0)
	v_fmac_f32_e32 v56, v30, v68
	v_fmac_f32_e32 v56, v31, v69
	v_fmac_f32_e32 v56, v28, v70
	v_fmac_f32_e32 v56, v29, v71
	v_mul_f32_e64 v57, |v56|, s2
	v_exp_f32_e32 v57, v57
	v_min_f32_e32 v56, 0, v56
	v_add_f32_e32 v57, 1.0, v57
	v_cmp_gt_f32_e32 vcc, s70, v57
	s_nop 1
	v_cndmask_b32_e64 v58, 0, 32, vcc
	v_ldexp_f32 v57, v57, v58
	v_log_f32_e32 v57, v57
	v_cndmask_b32_e32 v58, 0, v73, vcc
	v_mul_f32_e32 v59, 0x3f317217, v57
	v_fma_f32 v59, v57, s3, -v59
	v_fmac_f32_e32 v59, 0x3377d1cf, v57
	v_fmac_f32_e32 v59, 0x3f317217, v57
	v_cmp_lt_f32_e64 vcc, |v57|, s6
	s_nop 1
	v_cndmask_b32_e32 v57, v57, v59, vcc
	v_sub_f32_e32 v57, v57, v58
	v_sub_f32_e32 v56, v56, v57
	v_fmac_f32_e32 v54, 0x3d800000, v56
	ds_write_b32 v55, v54 offset:1300
	ds_read_b128 v[56:59], v53 offset:17472
	ds_read_b128 v[60:63], v53 offset:17488
	ds_read_b128 v[64:67], v53 offset:17504
	ds_read_b128 v[68:71], v53 offset:17520
	s_waitcnt lgkmcnt(3)
	v_fma_f32 v56, v44, v56, v50
	v_fmac_f32_e32 v56, v45, v57
	v_fmac_f32_e32 v56, v42, v58
	v_fmac_f32_e32 v56, v43, v59
	s_waitcnt lgkmcnt(2)
	v_fmac_f32_e32 v56, v38, v60
	v_fmac_f32_e32 v56, v39, v61
	v_fmac_f32_e32 v56, v36, v62
	v_fmac_f32_e32 v56, v37, v63
	s_waitcnt lgkmcnt(1)
	v_fmac_f32_e32 v56, v34, v64
	v_fmac_f32_e32 v56, v35, v65
	v_fmac_f32_e32 v56, v32, v66
	v_fmac_f32_e32 v56, v33, v67
	s_waitcnt lgkmcnt(0)
	v_fmac_f32_e32 v56, v30, v68
	v_fmac_f32_e32 v56, v31, v69
	v_fmac_f32_e32 v56, v28, v70
	v_fmac_f32_e32 v56, v29, v71
	v_mul_f32_e64 v57, |v56|, s2
	v_exp_f32_e32 v57, v57
	v_min_f32_e32 v56, 0, v56
	v_add_f32_e32 v57, 1.0, v57
	v_cmp_gt_f32_e32 vcc, s70, v57
	s_nop 1
	v_cndmask_b32_e64 v58, 0, 32, vcc
	v_ldexp_f32 v57, v57, v58
	v_log_f32_e32 v57, v57
	v_cndmask_b32_e32 v58, 0, v73, vcc
	v_mul_f32_e32 v59, 0x3f317217, v57
	v_fma_f32 v59, v57, s3, -v59
	v_fmac_f32_e32 v59, 0x3377d1cf, v57
	v_fmac_f32_e32 v59, 0x3f317217, v57
	v_cmp_lt_f32_e64 vcc, |v57|, s6
	s_nop 1
	v_cndmask_b32_e32 v57, v57, v59, vcc
	v_sub_f32_e32 v57, v57, v58
	v_sub_f32_e32 v56, v56, v57
	v_fmac_f32_e32 v54, 0x3d800000, v56
	ds_write_b32 v55, v54 offset:1560
	ds_read_b128 v[56:59], v53 offset:17536
	ds_read_b128 v[60:63], v53 offset:17552
	ds_read_b128 v[64:67], v53 offset:17568
	ds_read_b128 v[68:71], v53 offset:17584
	s_waitcnt lgkmcnt(3)
	v_fma_f32 v56, v44, v56, v50
	v_fmac_f32_e32 v56, v45, v57
	v_fmac_f32_e32 v56, v42, v58
	v_fmac_f32_e32 v56, v43, v59
	s_waitcnt lgkmcnt(2)
	v_fmac_f32_e32 v56, v38, v60
	v_fmac_f32_e32 v56, v39, v61
	v_fmac_f32_e32 v56, v36, v62
	v_fmac_f32_e32 v56, v37, v63
	s_waitcnt lgkmcnt(1)
	v_fmac_f32_e32 v56, v34, v64
	v_fmac_f32_e32 v56, v35, v65
	v_fmac_f32_e32 v56, v32, v66
	v_fmac_f32_e32 v56, v33, v67
	s_waitcnt lgkmcnt(0)
	v_fmac_f32_e32 v56, v30, v68
	v_fmac_f32_e32 v56, v31, v69
	v_fmac_f32_e32 v56, v28, v70
	v_fmac_f32_e32 v56, v29, v71
	v_mul_f32_e64 v57, |v56|, s2
	v_exp_f32_e32 v57, v57
	v_min_f32_e32 v56, 0, v56
	v_add_f32_e32 v57, 1.0, v57
	v_cmp_gt_f32_e32 vcc, s70, v57
	s_nop 1
	v_cndmask_b32_e64 v58, 0, 32, vcc
	v_ldexp_f32 v57, v57, v58
	v_log_f32_e32 v57, v57
	v_cndmask_b32_e32 v58, 0, v73, vcc
	v_mul_f32_e32 v59, 0x3f317217, v57
	v_fma_f32 v59, v57, s3, -v59
	v_fmac_f32_e32 v59, 0x3377d1cf, v57
	v_fmac_f32_e32 v59, 0x3f317217, v57
	v_cmp_lt_f32_e64 vcc, |v57|, s6
	s_nop 1
	v_cndmask_b32_e32 v57, v57, v59, vcc
	v_sub_f32_e32 v57, v57, v58
	v_sub_f32_e32 v56, v56, v57
	v_fmac_f32_e32 v54, 0x3d800000, v56
	ds_write_b32 v55, v54 offset:1820
	ds_read_b128 v[56:59], v53 offset:17600
	ds_read_b128 v[60:63], v53 offset:17616
	ds_read_b128 v[64:67], v53 offset:17632
	ds_read_b128 v[68:71], v53 offset:17648
	s_waitcnt lgkmcnt(3)
	v_fmac_f32_e32 v50, v44, v56
	v_fmac_f32_e32 v50, v45, v57
	v_fmac_f32_e32 v50, v42, v58
	v_fmac_f32_e32 v50, v43, v59
	s_waitcnt lgkmcnt(2)
	v_fmac_f32_e32 v50, v38, v60
	v_fmac_f32_e32 v50, v39, v61
	v_fmac_f32_e32 v50, v36, v62
	v_fmac_f32_e32 v50, v37, v63
	s_waitcnt lgkmcnt(1)
	v_fmac_f32_e32 v50, v34, v64
	v_fmac_f32_e32 v50, v35, v65
	v_fmac_f32_e32 v50, v32, v66
	v_fmac_f32_e32 v50, v33, v67
	s_waitcnt lgkmcnt(0)
	v_fmac_f32_e32 v50, v30, v68
	v_fmac_f32_e32 v50, v31, v69
	v_fmac_f32_e32 v50, v28, v70
	v_fmac_f32_e32 v50, v29, v71
	v_mul_f32_e64 v28, |v50|, s2
	v_exp_f32_e32 v28, v28
	s_nop 0
	v_add_f32_e32 v28, 1.0, v28
	v_cmp_gt_f32_e32 vcc, s70, v28
	s_nop 1
	v_cndmask_b32_e64 v29, 0, 32, vcc
	v_ldexp_f32 v28, v28, v29
	v_log_f32_e32 v28, v28
	v_cndmask_b32_e32 v30, 0, v73, vcc
	v_min_f32_e32 v29, 0, v50
	v_mul_f32_e32 v31, 0x3f317217, v28
	v_fma_f32 v31, v28, s3, -v31
	v_fmac_f32_e32 v31, 0x3377d1cf, v28
	v_fmac_f32_e32 v31, 0x3f317217, v28
	v_cmp_lt_f32_e64 vcc, |v28|, s6
	s_nop 1
	v_cndmask_b32_e32 v28, v28, v31, vcc
	v_sub_f32_e32 v28, v28, v30
	v_sub_f32_e32 v28, v29, v28
	v_fmac_f32_e32 v54, 0x3d800000, v28
	v_cmp_lt_i32_e32 vcc, 0, v25
	ds_write_b32 v55, v54 offset:2080
	ds_write_b32 v27, v54
	s_waitcnt lgkmcnt(0)
	s_barrier
	s_and_saveexec_b64 s[2:3], vcc
	s_cbranch_execz .LBB0_313
	s_add_i32 s6, 0, 0x1e100
	v_lshl_add_u32 v28, v40, 2, s6
	v_mov_b32_e32 v27, 0
	s_mov_b64 s[6:7], 0
	v_mov_b32_e32 v29, v25

.LBB0_337:
	v_readlane_b32 s2, v255, 47
	v_readlane_b32 s3, v255, 48
	s_mov_b32 s6, s2
	v_readlane_b32 s72, v253, 6
	s_mul_i32 s3, s6, 0x1078000
	v_readlane_b32 s86, v253, 20
	s_mul_hi_i32 s2, s2, 0x1078000
	v_readlane_b32 s87, v253, 21
	s_add_u32 s42, s86, s3
	s_addc_u32 s43, s87, s2
	v_readlane_b32 s2, v255, 45
	s_lshl_b32 s44, s2, 3
	s_cmp_gt_i32 s41, 0
	s_mov_b32 s48, 0
	s_cselect_b64 s[2:3], -1, 0
	s_cmp_lt_i32 s41, 1
	s_mov_b32 s8, 0
	v_readlane_b32 s73, v253, 7
	v_readlane_b32 s74, v253, 8
	v_readlane_b32 s75, v253, 9
	v_readlane_b32 s76, v253, 10
	v_readlane_b32 s77, v253, 11
	v_readlane_b32 s78, v253, 12
	v_readlane_b32 s79, v253, 13
	v_readlane_b32 s80, v253, 14
	v_readlane_b32 s81, v253, 15
	v_readlane_b32 s82, v253, 16
	v_readlane_b32 s83, v253, 17
	v_readlane_b32 s84, v253, 18
	v_readlane_b32 s85, v253, 19
	s_cbranch_scc1 .LBB0_339
	v_readlane_b32 s7, v255, 44
	s_lshr_b32 s6, s7, 3
	s_cmp_eq_u32 s6, 0
	s_cbranch_scc0 .Ltpa_1
	s_add_i32 s7, s7, 24
	s_branch .Ltpa_done
.Ltpa_1:
	s_cmp_eq_u32 s6, 1
	s_cbranch_scc0 .Ltpa_3
	s_add_i32 s7, s7, 48
	s_branch .Ltpa_done
.Ltpa_3:
	s_cmp_eq_u32 s6, 3
	s_cbranch_scc0 .Ltpa_7
	s_add_i32 s7, s7, -24
	s_branch .Ltpa_done
.Ltpa_7:
	s_cmp_eq_u32 s6, 7
	s_cbranch_scc0 .Ltpa_done
	s_add_i32 s7, s7, -48
.Ltpa_done:
	s_and_b32 s6, s7, 7
	s_or_b32 s6, s44, s6
	s_ashr_i32 s7, s7, 3
	s_and_b64 s[4:5], s[4:5], exec
	v_readlane_b32 s4, v254, 27
	s_cselect_b32 s48, s7, s4
	v_readlane_b32 s4, v254, 26
	s_cselect_b32 s8, s6, s4
	s_mul_i32 s4, s8, 0x88000
	v_readlane_b32 s6, v253, 27
	v_mbcnt_lo_u32_b32 v1, -1, 0
	v_mbcnt_hi_u32_b32 v1, -1, v1
	v_readlane_b32 s9, v253, 22
	s_mul_hi_i32 s5, s8, 0x88000
	v_readlane_b32 s7, v253, 28
	s_add_u32 s4, s6, s4
	v_or_b32_e32 v2, s9, v1
	v_lshlrev_b32_e32 v1, 4, v1
	s_addc_u32 s5, s7, s5
	v_and_b32_e32 v40, 0x70, v1
	v_ashrrev_i32_e32 v8, 3, v2
	v_lshl_add_u64 v[2:3], s[4:5], 0, v[40:41]
	v_mad_i64_i32 v[4:5], s[4:5], v8, s33, v[2:3]
	v_add_u32_e32 v1, 32, v8
	v_add_u32_e32 v9, 64, v8
	s_mul_i32 s6, s48, 0x88000
	v_mad_i64_i32 v[6:7], s[4:5], v1, s33, v[2:3]
	global_load_dwordx4 v[58:61], v[4:5], off
	global_load_dwordx4 v[54:57], v[6:7], off
	v_mad_i64_i32 v[4:5], s[4:5], v9, s33, v[2:3]
	v_add_u32_e32 v10, 0x60, v8
	v_add_u32_e32 v11, 0x80, v8
	s_mul_hi_i32 s7, s48, 0x88000
	s_add_u32 s6, s42, s6
	v_mad_i64_i32 v[6:7], s[4:5], v10, s33, v[2:3]
	global_load_dwordx4 v[66:69], v[4:5], off
	global_load_dwordx4 v[62:65], v[6:7], off
	v_mad_i64_i32 v[4:5], s[4:5], v11, s33, v[2:3]
	v_add_u32_e32 v12, 0xa0, v8
	v_add_u32_e32 v13, 0xc0, v8
	v_add_u32_e32 v14, 0xe0, v8
	s_addc_u32 s7, s43, s7
	v_mad_i64_i32 v[6:7], s[4:5], v12, s33, v[2:3]
	global_load_dwordx4 v[70:73], v[4:5], off
	global_load_dwordx4 v[74:77], v[6:7], off
	v_mad_i64_i32 v[4:5], s[4:5], v13, s33, v[2:3]
	v_mad_i64_i32 v[2:3], s[4:5], v14, s33, v[2:3]
	global_load_dwordx4 v[84:87], v[4:5], off
	global_load_dwordx4 v[88:91], v[2:3], off
	v_lshl_add_u64 v[2:3], s[6:7], 0, v[40:41]
	v_mad_i64_i32 v[4:5], s[4:5], v8, s33, v[2:3]
	v_mad_i64_i32 v[6:7], s[4:5], v1, s33, v[2:3]
	global_load_dwordx4 v[92:95], v[4:5], off
	global_load_dwordx4 v[96:99], v[6:7], off
	v_mad_i64_i32 v[4:5], s[4:5], v9, s33, v[2:3]
	v_mad_i64_i32 v[6:7], s[4:5], v10, s33, v[2:3]
	global_load_dwordx4 v[100:103], v[4:5], off
	global_load_dwordx4 v[104:107], v[6:7], off
	v_mad_i64_i32 v[4:5], s[4:5], v11, s33, v[2:3]
	v_mad_i64_i32 v[6:7], s[4:5], v12, s33, v[2:3]
	global_load_dwordx4 v[108:111], v[4:5], off
	global_load_dwordx4 v[112:115], v[6:7], off
	v_mad_i64_i32 v[4:5], s[4:5], v13, s33, v[2:3]
	v_mad_i64_i32 v[2:3], s[4:5], v14, s33, v[2:3]
	global_load_dwordx4 v[116:119], v[4:5], off
	global_load_dwordx4 v[120:123], v[2:3], off

.LBB0_347:
	s_andn2_b64 vcc, exec, s[2:3]
	s_cbranch_vccnz .LBB0_349
	s_mul_i32 s2, s45, s40
	v_readlane_b32 s3, v255, 44
	s_add_i32 s2, s2, s3
	s_lshr_b32 s3, s2, 3
	s_cmp_eq_u32 s3, 0
	s_cbranch_scc0 .Ltpb_1
	s_add_i32 s2, s2, 24
	s_branch .Ltpb_done
.Ltpb_1:
	s_cmp_eq_u32 s3, 1
	s_cbranch_scc0 .Ltpb_3
	s_add_i32 s2, s2, 48
	s_branch .Ltpb_done
.Ltpb_3:
	s_cmp_eq_u32 s3, 3
	s_cbranch_scc0 .Ltpb_7
	s_add_i32 s2, s2, -24
	s_branch .Ltpb_done
.Ltpb_7:
	s_cmp_eq_u32 s3, 7
	s_cbranch_scc0 .Ltpb_done
	s_add_i32 s2, s2, -48
.Ltpb_done:
	s_and_b32 s3, s2, 7
	s_or_b32 s46, s3, s44
	s_ashr_i32 s47, s2, 3
